# speedup vs baseline: 1.0208x; 1.0038x over previous
; DEVI void sub_barrier(unsigned* cnt, unsigned target, int tid) {
;     ...
;     unsigned spins = 0;
;     while (__hip_atomic_load(cnt, __ATOMIC_RELAXED, __HIP_MEMORY_SCOPE_AGENT) < target) {
;       __builtin_amdgcn_s_sleep(4);
;       if (++spins > (1u << 24)) break;
;     }
; __global__ __launch_bounds__(512, 2) void mega(Params p_arg, int lo, int hi) {
;     ...
;             sub_barrier(cnt, 128u, TID_);
;             if (b < 64) hgrn_scan_item(TID_, BID_, p, g, b);
;             sub_barrier(cnt, 256u, TID_);
.LBB0_161:
	global_load_dword v0, v197, s[6:7] sc1
	s_mov_b64 s[12:13], -1
	s_waitcnt vmcnt(0)
	v_cmp_lt_u32_e32 vcc, s23, v0
	s_cbranch_vccnz .LBB0_160
	s_cmp_lg_u32 s14, 0
	s_sleep 32
	s_cbranch_scc0 .LBB0_159
	global_load_dword v0, v197, s[6:7] sc1
	s_movk_i32 s1, 0x80
	s_waitcnt vmcnt(0)
	v_cmp_gt_u32_e32 vcc, s1, v0
	s_cbranch_vccz .LBB0_160
	s_sleep 32
	global_load_dword v0, v197, s[6:7] sc1
	s_waitcnt vmcnt(0)
	v_cmp_gt_u32_e32 vcc, s1, v0
	s_cbranch_vccz .LBB0_160
	s_sleep 32
	global_load_dword v0, v197, s[6:7] sc1
	s_waitcnt vmcnt(0)
	v_cmp_gt_u32_e32 vcc, s1, v0
	s_cbranch_vccz .LBB0_160
	s_sleep 32
	global_load_dword v0, v197, s[6:7] sc1
	s_waitcnt vmcnt(0)
	v_cmp_gt_u32_e32 vcc, s1, v0
	s_cbranch_vccz .LBB0_160
	s_sleep 32
	global_load_dword v0, v197, s[6:7] sc1
	s_waitcnt vmcnt(0)
	v_cmp_gt_u32_e32 vcc, s1, v0
	s_cbranch_vccz .LBB0_160
	s_sleep 32
	global_load_dword v0, v197, s[6:7] sc1
	s_waitcnt vmcnt(0)
	v_cmp_gt_u32_e32 vcc, s1, v0
	s_cbranch_vccz .LBB0_160
	s_sleep 32
	global_load_dword v0, v197, s[6:7] sc1
	s_waitcnt vmcnt(0)
	v_cmp_gt_u32_e32 vcc, s1, v0
	s_cbranch_vccz .LBB0_160
	s_sleep 32
	s_add_i32 s14, s14, -8
	s_mov_b64 s[12:13], 0
	s_branch .LBB0_160

; DEVI void sub_barrier(unsigned* cnt, unsigned target, int tid) {
;     ...
;     unsigned spins = 0;
;     while (__hip_atomic_load(cnt, __ATOMIC_RELAXED, __HIP_MEMORY_SCOPE_AGENT) < target) {
;       __builtin_amdgcn_s_sleep(4);
;       if (++spins > (1u << 24)) break;
;     }
; __global__ __launch_bounds__(512, 2) void mega(Params p_arg, int lo, int hi) {
;     ...
;             sub_barrier(cnt, 128u, TID_);
;             if (b < 64) hgrn_scan_item(TID_, BID_, p, g, b);
;             sub_barrier(cnt, 256u, TID_);
.LBB0_182:
	global_load_dword v0, v197, s[6:7] sc1
	s_mov_b64 s[4:5], -1
	s_waitcnt vmcnt(0)
	v_cmp_lt_u32_e32 vcc, s0, v0
	s_cbranch_vccnz .LBB0_181
	s_cmp_lg_u32 s12, 0
	s_sleep 32
	s_cbranch_scc0 .LBB0_180
	global_load_dword v0, v197, s[6:7] sc1
	s_waitcnt vmcnt(0)
	v_cmp_gt_u32_e32 vcc, s47, v0
	s_cbranch_vccz .LBB0_181
	s_sleep 32
	global_load_dword v0, v197, s[6:7] sc1
	s_waitcnt vmcnt(0)
	v_cmp_gt_u32_e32 vcc, s47, v0
	s_cbranch_vccz .LBB0_181
	s_sleep 32
	global_load_dword v0, v197, s[6:7] sc1
	s_waitcnt vmcnt(0)
	v_cmp_gt_u32_e32 vcc, s47, v0
	s_cbranch_vccz .LBB0_181
	s_sleep 32
	global_load_dword v0, v197, s[6:7] sc1
	s_waitcnt vmcnt(0)
	v_cmp_gt_u32_e32 vcc, s47, v0
	s_cbranch_vccz .LBB0_181
	s_sleep 32
	global_load_dword v0, v197, s[6:7] sc1
	s_waitcnt vmcnt(0)
	v_cmp_gt_u32_e32 vcc, s47, v0
	s_cbranch_vccz .LBB0_181
	s_sleep 32
	global_load_dword v0, v197, s[6:7] sc1
	s_waitcnt vmcnt(0)
	v_cmp_gt_u32_e32 vcc, s47, v0
	s_cbranch_vccz .LBB0_181
	s_sleep 32
	global_load_dword v0, v197, s[6:7] sc1
	s_waitcnt vmcnt(0)
	v_cmp_gt_u32_e32 vcc, s47, v0
	s_cbranch_vccz .LBB0_181
	s_sleep 32
	s_add_i32 s12, s12, -8
	s_mov_b64 s[4:5], 0
	s_branch .LBB0_181

; DEVI float sigm(float x) { return 1.f / (1.f + __expf(-x)); }
; DEVI void rwkv_pre_tile(int TID_, int BID_, PREF p, int g, int tile, char* shm) {
;     ...
; #pragma unroll
;       for (int nt = 0; nt < 8; ++nt) {
;         int col = w * 128 + 16 * nt + fr;
;         const u16* wp = lw + (size_t)lo * 65536 + (size_t)col * 64 + fq * 8;
;         bf16x8 b0 = *(const bf16x8*)wp, b1 = *(const bf16x8*)(wp + 32);
;         f32x4 acc = (f32x4){0.f, 0.f, 0.f, 0.f};
;         acc = __builtin_amdgcn_mfma_f32_16x16x32_bf16(a0, b0, acc, 0, 0, 0);
;         acc = __builtin_amdgcn_mfma_f32_16x16x32_bf16(a1, b1, acc, 0, 0, 0);
;         float bv = bias[col];
; #pragma unroll
;         for (int r = 0; r < 4; ++r) {
;           float sg = sigm(bv + acc[r]);
;           if (lo < 2) sg *= 0.60653066f;
;           resL[(size_t)(lo * 16 + fq * 4 + r) * 1024 + col] = f2h(sg);
;         }
;       }
.LBB0_368:
	v_lshl_add_u64 v[8:9], v[82:83], 0, s[88:89]
	v_add_co_u32_e32 v84, vcc, 0xca01000, v8
	ds_read_b128 v[0:3], v145
	ds_read_b128 v[4:7], v145 offset:64
	v_addc_co_u32_e32 v85, vcc, 0, v9, vcc
	global_load_dwordx4 v[8:11], v[84:85], off
	global_load_dwordx4 v[148:151], v[84:85], off offset:64
	s_waitcnt lgkmcnt(0)
	v_lshl_add_u64 v[84:85], v[34:35], 2, s[48:49]
	global_load_dword v147, v[84:85], off
	v_lshl_add_u64 v[232:233], v[80:81], 0, s[88:89]
	v_add_co_u32_e32 v232, vcc, 0xca01000, v232
	s_nop 1
	v_addc_co_u32_e32 v233, vcc, 0, v233, vcc
	global_load_dwordx4 v[184:187], v[232:233], off
	global_load_dwordx4 v[188:191], v[232:233], off offset:64
	global_load_dword v228, v[84:85], off offset:64
	v_lshl_add_u64 v[232:233], v[78:79], 0, s[88:89]
	v_add_co_u32_e32 v232, vcc, 0xca01000, v232
	s_nop 1
	v_addc_co_u32_e32 v233, vcc, 0, v233, vcc
	global_load_dwordx4 v[192:195], v[232:233], off
	global_load_dwordx4 v[216:219], v[232:233], off offset:64
	global_load_dword v229, v[84:85], off offset:128
	v_lshl_add_u64 v[232:233], v[76:77], 0, s[88:89]
	v_add_co_u32_e32 v232, vcc, 0xca01000, v232
	s_nop 1
	v_addc_co_u32_e32 v233, vcc, 0, v233, vcc
	global_load_dwordx4 v[220:223], v[232:233], off
	global_load_dwordx4 v[224:227], v[232:233], off offset:64
	global_load_dword v230, v[84:85], off offset:192
	s_cmp_eq_u32 s88, 0x40000
	s_cselect_b64 s[54:55], -1, 0
	s_add_i32 s4, s4, 1
	v_add_u32_e32 v145, 0x80, v145
	s_waitcnt vmcnt(2)
	v_mfma_f32_16x16x32_bf16 v[8:11], v[0:3], v[8:11], 0
	s_waitcnt vmcnt(1)
	v_mfma_f32_16x16x32_bf16 v[8:11], v[4:7], v[148:151], v[8:11]
	s_waitcnt vmcnt(0)
	s_nop 6
	v_add_f32_e32 v8, v147, v8
	v_mul_f32_e32 v8, 0xbfb8aa3b, v8
	v_exp_f32_e32 v8, v8
	s_nop 0
	v_add_f32_e32 v8, 1.0, v8
	v_div_scale_f32 v148, s[38:39], v8, v8, 1.0
	v_rcp_f32_e32 v149, v148
	s_nop 0
	v_fma_f32 v150, -v148, v149, 1.0
	v_fmac_f32_e32 v149, v150, v149
	v_div_scale_f32 v150, vcc, 1.0, v8, 1.0
	v_mul_f32_e32 v151, v150, v149
	v_fma_f32 v152, -v148, v151, v150
	v_fmac_f32_e32 v151, v152, v149
	v_fma_f32 v148, -v148, v151, v150
	v_div_fmas_f32 v148, v148, v149, v151
	v_div_fixup_f32 v8, v148, v8, 1.0
	v_mul_f32_e32 v148, 0x3f1b4598, v8
	v_cndmask_b32_e64 v8, v148, v8, s[54:55]
	v_cvt_f16_f32_e32 v8, v8
	ds_write_b16 v146, v8
	v_add_f32_e32 v8, v147, v9
	v_mul_f32_e32 v8, 0xbfb8aa3b, v8
	v_exp_f32_e32 v8, v8
	s_nop 0
	v_add_f32_e32 v8, 1.0, v8
	v_div_scale_f32 v9, s[38:39], v8, v8, 1.0
	v_rcp_f32_e32 v148, v9
	s_nop 0
	v_fma_f32 v149, -v9, v148, 1.0
	v_fmac_f32_e32 v148, v149, v148
	v_div_scale_f32 v149, vcc, 1.0, v8, 1.0
	v_mul_f32_e32 v150, v149, v148
	v_fma_f32 v151, -v9, v150, v149
	v_fmac_f32_e32 v150, v151, v148
	v_fma_f32 v9, -v9, v150, v149
	v_div_fmas_f32 v9, v9, v148, v150
	v_div_fixup_f32 v8, v9, v8, 1.0
	v_mul_f32_e32 v9, 0x3f1b4598, v8
	v_cndmask_b32_e64 v8, v9, v8, s[54:55]
	v_cvt_f16_f32_e32 v8, v8
	ds_write_b16 v146, v8 offset:2048
	v_add_f32_e32 v8, v147, v10
	v_mul_f32_e32 v8, 0xbfb8aa3b, v8
	v_exp_f32_e32 v8, v8
	s_nop 0
	v_add_f32_e32 v8, 1.0, v8
	v_div_scale_f32 v9, s[38:39], v8, v8, 1.0
	v_rcp_f32_e32 v10, v9
	s_nop 0
	v_fma_f32 v148, -v9, v10, 1.0
	v_fmac_f32_e32 v10, v148, v10
	v_div_scale_f32 v148, vcc, 1.0, v8, 1.0
	v_mul_f32_e32 v149, v148, v10
	v_fma_f32 v150, -v9, v149, v148
	v_fmac_f32_e32 v149, v150, v10
	v_fma_f32 v9, -v9, v149, v148
	v_div_fmas_f32 v9, v9, v10, v149
	v_div_fixup_f32 v8, v9, v8, 1.0
	v_mul_f32_e32 v9, 0x3f1b4598, v8
	v_cndmask_b32_e64 v8, v9, v8, s[54:55]
	v_cvt_f16_f32_e32 v8, v8
	ds_write_b16 v146, v8 offset:4096
	v_add_f32_e32 v8, v147, v11
	v_mul_f32_e32 v8, 0xbfb8aa3b, v8
	v_exp_f32_e32 v8, v8
	s_nop 0
	v_add_f32_e32 v8, 1.0, v8
	v_div_scale_f32 v9, s[38:39], v8, v8, 1.0
	v_rcp_f32_e32 v10, v9
	s_nop 0
	v_fma_f32 v11, -v9, v10, 1.0
	v_fmac_f32_e32 v10, v11, v10
	v_div_scale_f32 v11, vcc, 1.0, v8, 1.0
	v_mul_f32_e32 v147, v11, v10
	v_fma_f32 v148, -v9, v147, v11
	v_fmac_f32_e32 v147, v148, v10
	v_fma_f32 v9, -v9, v147, v11
	v_div_fmas_f32 v9, v9, v10, v147
	v_div_fixup_f32 v8, v9, v8, 1.0
	v_mul_f32_e32 v9, 0x3f1b4598, v8
	v_cndmask_b32_e64 v8, v9, v8, s[54:55]
	v_cvt_f16_f32_e32 v8, v8
	ds_write_b16 v146, v8 offset:6144
	v_lshl_add_u64 v[8:9], v[80:81], 0, s[88:89]
	v_add_co_u32_e32 v148, vcc, s70, v8
	s_nop 1
	v_addc_co_u32_e32 v149, vcc, 0, v9, vcc
	s_nop 0
	s_waitcnt vmcnt(1)
	v_mfma_f32_16x16x32_bf16 v[8:11], v[0:3], v[184:187], 0
	s_waitcnt vmcnt(1)
	v_mfma_f32_16x16x32_bf16 v[8:11], v[4:7], v[188:191], v[8:11]
	s_waitcnt vmcnt(0)
; DEVI float sigm(float x) { return 1.f / (1.f + __expf(-x)); }
; DEVI void rwkv_pre_tile(int TID_, int BID_, PREF p, int g, int tile, char* shm) {
;     ...
; #pragma unroll
;       for (int nt = 0; nt < 8; ++nt) {
;         int col = w * 128 + 16 * nt + fr;
;         const u16* wp = lw + (size_t)lo * 65536 + (size_t)col * 64 + fq * 8;
;         bf16x8 b0 = *(const bf16x8*)wp, b1 = *(const bf16x8*)(wp + 32);
;         f32x4 acc = (f32x4){0.f, 0.f, 0.f, 0.f};
;         acc = __builtin_amdgcn_mfma_f32_16x16x32_bf16(a0, b0, acc, 0, 0, 0);
;         acc = __builtin_amdgcn_mfma_f32_16x16x32_bf16(a1, b1, acc, 0, 0, 0);
;         float bv = bias[col];
; #pragma unroll
;         for (int r = 0; r < 4; ++r) {
;           float sg = sigm(bv + acc[r]);
;           if (lo < 2) sg *= 0.60653066f;
;           resL[(size_t)(lo * 16 + fq * 4 + r) * 1024 + col] = f2h(sg);
;         }
;       }
	s_nop 6
	v_add_f32_e32 v8, v228, v8
	v_mul_f32_e32 v8, 0xbfb8aa3b, v8
	v_exp_f32_e32 v8, v8
	s_nop 0
	v_add_f32_e32 v8, 1.0, v8
	v_div_scale_f32 v148, s[38:39], v8, v8, 1.0
	v_rcp_f32_e32 v149, v148
	s_nop 0
	v_fma_f32 v150, -v148, v149, 1.0
	v_fmac_f32_e32 v149, v150, v149
	v_div_scale_f32 v150, vcc, 1.0, v8, 1.0
	v_mul_f32_e32 v151, v150, v149
	v_fma_f32 v152, -v148, v151, v150
	v_fmac_f32_e32 v151, v152, v149
	v_fma_f32 v148, -v148, v151, v150
	v_div_fmas_f32 v148, v148, v149, v151
	v_div_fixup_f32 v8, v148, v8, 1.0
	v_mul_f32_e32 v148, 0x3f1b4598, v8
	v_cndmask_b32_e64 v8, v148, v8, s[54:55]
	v_cvt_f16_f32_e32 v8, v8
	ds_write_b16 v146, v8 offset:32
	v_add_f32_e32 v8, v228, v9
	v_mul_f32_e32 v8, 0xbfb8aa3b, v8
	v_exp_f32_e32 v8, v8
	s_nop 0
	v_add_f32_e32 v8, 1.0, v8
	v_div_scale_f32 v9, s[38:39], v8, v8, 1.0
	v_rcp_f32_e32 v148, v9
	s_nop 0
	v_fma_f32 v149, -v9, v148, 1.0
	v_fmac_f32_e32 v148, v149, v148
	v_div_scale_f32 v149, vcc, 1.0, v8, 1.0
	v_mul_f32_e32 v150, v149, v148
	v_fma_f32 v151, -v9, v150, v149
	v_fmac_f32_e32 v150, v151, v148
	v_fma_f32 v9, -v9, v150, v149
	v_div_fmas_f32 v9, v9, v148, v150
	v_div_fixup_f32 v8, v9, v8, 1.0
	v_mul_f32_e32 v9, 0x3f1b4598, v8
	v_cndmask_b32_e64 v8, v9, v8, s[54:55]
	v_cvt_f16_f32_e32 v8, v8
	ds_write_b16 v146, v8 offset:2080
	v_add_f32_e32 v8, v228, v10
	v_mul_f32_e32 v8, 0xbfb8aa3b, v8
	v_exp_f32_e32 v8, v8
	s_nop 0
	v_add_f32_e32 v8, 1.0, v8
	v_div_scale_f32 v9, s[38:39], v8, v8, 1.0
	v_rcp_f32_e32 v10, v9
	s_nop 0
	v_fma_f32 v148, -v9, v10, 1.0
	v_fmac_f32_e32 v10, v148, v10
	v_div_scale_f32 v148, vcc, 1.0, v8, 1.0
	v_mul_f32_e32 v149, v148, v10
	v_fma_f32 v150, -v9, v149, v148
	v_fmac_f32_e32 v149, v150, v10
	v_fma_f32 v9, -v9, v149, v148
	v_div_fmas_f32 v9, v9, v10, v149
	v_div_fixup_f32 v8, v9, v8, 1.0
	v_mul_f32_e32 v9, 0x3f1b4598, v8
	v_cndmask_b32_e64 v8, v9, v8, s[54:55]
	v_cvt_f16_f32_e32 v8, v8
	ds_write_b16 v146, v8 offset:4128
	v_add_f32_e32 v8, v228, v11
	v_mul_f32_e32 v8, 0xbfb8aa3b, v8
	v_exp_f32_e32 v8, v8
	s_nop 0
	v_add_f32_e32 v8, 1.0, v8
	v_div_scale_f32 v9, s[38:39], v8, v8, 1.0
	v_rcp_f32_e32 v10, v9
	s_nop 0
	v_fma_f32 v11, -v9, v10, 1.0
	v_fmac_f32_e32 v10, v11, v10
	v_div_scale_f32 v11, vcc, 1.0, v8, 1.0
	v_mul_f32_e32 v147, v11, v10
	v_fma_f32 v148, -v9, v147, v11
	v_fmac_f32_e32 v147, v148, v10
	v_fma_f32 v9, -v9, v147, v11
	v_div_fmas_f32 v9, v9, v10, v147
	v_div_fixup_f32 v8, v9, v8, 1.0
	v_mul_f32_e32 v9, 0x3f1b4598, v8
	v_cndmask_b32_e64 v8, v9, v8, s[54:55]
	v_cvt_f16_f32_e32 v8, v8
	ds_write_b16 v146, v8 offset:6176
	v_lshl_add_u64 v[8:9], v[78:79], 0, s[88:89]
	v_add_co_u32_e32 v148, vcc, s70, v8
	s_nop 1
	v_addc_co_u32_e32 v149, vcc, 0, v9, vcc
	s_nop 0
	s_waitcnt vmcnt(1)
	v_mfma_f32_16x16x32_bf16 v[8:11], v[0:3], v[192:195], 0
	s_waitcnt vmcnt(1)
	v_mfma_f32_16x16x32_bf16 v[8:11], v[4:7], v[216:219], v[8:11]
	s_waitcnt vmcnt(0)
	s_nop 6
	v_add_f32_e32 v8, v229, v8
	v_mul_f32_e32 v8, 0xbfb8aa3b, v8
	v_exp_f32_e32 v8, v8
	s_nop 0
	v_add_f32_e32 v8, 1.0, v8
	v_div_scale_f32 v148, s[38:39], v8, v8, 1.0
	v_rcp_f32_e32 v149, v148
	s_nop 0
	v_fma_f32 v150, -v148, v149, 1.0
	v_fmac_f32_e32 v149, v150, v149
	v_div_scale_f32 v150, vcc, 1.0, v8, 1.0
	v_mul_f32_e32 v151, v150, v149
	v_fma_f32 v152, -v148, v151, v150
	v_fmac_f32_e32 v151, v152, v149
	v_fma_f32 v148, -v148, v151, v150
	v_div_fmas_f32 v148, v148, v149, v151
	v_div_fixup_f32 v8, v148, v8, 1.0
	v_mul_f32_e32 v148, 0x3f1b4598, v8
	v_cndmask_b32_e64 v8, v148, v8, s[54:55]
	v_cvt_f16_f32_e32 v8, v8
	ds_write_b16 v146, v8 offset:64
	v_add_f32_e32 v8, v229, v9
	v_mul_f32_e32 v8, 0xbfb8aa3b, v8
	v_exp_f32_e32 v8, v8
	s_nop 0
	v_add_f32_e32 v8, 1.0, v8
	v_div_scale_f32 v9, s[38:39], v8, v8, 1.0
	v_rcp_f32_e32 v148, v9
	s_nop 0
	v_fma_f32 v149, -v9, v148, 1.0
	v_fmac_f32_e32 v148, v149, v148
	v_div_scale_f32 v149, vcc, 1.0, v8, 1.0
	v_mul_f32_e32 v150, v149, v148
	v_fma_f32 v151, -v9, v150, v149
	v_fmac_f32_e32 v150, v151, v148
	v_fma_f32 v9, -v9, v150, v149
	v_div_fmas_f32 v9, v9, v148, v150
	v_div_fixup_f32 v8, v9, v8, 1.0
	v_mul_f32_e32 v9, 0x3f1b4598, v8
	v_cndmask_b32_e64 v8, v9, v8, s[54:55]
	v_cvt_f16_f32_e32 v8, v8
	ds_write_b16 v146, v8 offset:2112
	v_add_f32_e32 v8, v229, v10
	v_mul_f32_e32 v8, 0xbfb8aa3b, v8
	v_exp_f32_e32 v8, v8
	s_nop 0
	v_add_f32_e32 v8, 1.0, v8
	v_div_scale_f32 v9, s[38:39], v8, v8, 1.0
	v_rcp_f32_e32 v10, v9
	s_nop 0
	v_fma_f32 v148, -v9, v10, 1.0
	v_fmac_f32_e32 v10, v148, v10
	v_div_scale_f32 v148, vcc, 1.0, v8, 1.0
	v_mul_f32_e32 v149, v148, v10
	v_fma_f32 v150, -v9, v149, v148
	v_fmac_f32_e32 v149, v150, v10
	v_fma_f32 v9, -v9, v149, v148
	v_div_fmas_f32 v9, v9, v10, v149
	v_div_fixup_f32 v8, v9, v8, 1.0
	v_mul_f32_e32 v9, 0x3f1b4598, v8
	v_cndmask_b32_e64 v8, v9, v8, s[54:55]
	v_cvt_f16_f32_e32 v8, v8
	ds_write_b16 v146, v8 offset:4160
	v_add_f32_e32 v8, v229, v11
	v_mul_f32_e32 v8, 0xbfb8aa3b, v8
	v_exp_f32_e32 v8, v8
	s_nop 0
	v_add_f32_e32 v8, 1.0, v8
	v_div_scale_f32 v9, s[38:39], v8, v8, 1.0
	v_rcp_f32_e32 v10, v9
	s_nop 0
	v_fma_f32 v11, -v9, v10, 1.0
	v_fmac_f32_e32 v10, v11, v10
	v_div_scale_f32 v11, vcc, 1.0, v8, 1.0
	v_mul_f32_e32 v147, v11, v10
	v_fma_f32 v148, -v9, v147, v11
	v_fmac_f32_e32 v147, v148, v10
	v_fma_f32 v9, -v9, v147, v11
	v_div_fmas_f32 v9, v9, v10, v147
	v_div_fixup_f32 v8, v9, v8, 1.0
	v_mul_f32_e32 v9, 0x3f1b4598, v8
	v_cndmask_b32_e64 v8, v9, v8, s[54:55]
	v_cvt_f16_f32_e32 v8, v8
	ds_write_b16 v146, v8 offset:6208
	v_lshl_add_u64 v[8:9], v[76:77], 0, s[88:89]
	v_add_co_u32_e32 v148, vcc, s70, v8
	s_nop 1
	v_addc_co_u32_e32 v149, vcc, 0, v9, vcc
	s_nop 0
	s_waitcnt vmcnt(1)
	v_mfma_f32_16x16x32_bf16 v[8:11], v[0:3], v[220:223], 0
	s_waitcnt vmcnt(1)
; DEVI float sigm(float x) { return 1.f / (1.f + __expf(-x)); }
; DEVI void rwkv_pre_tile(int TID_, int BID_, PREF p, int g, int tile, char* shm) {
;     ...
; #pragma unroll
;       for (int nt = 0; nt < 8; ++nt) {
;         int col = w * 128 + 16 * nt + fr;
;         const u16* wp = lw + (size_t)lo * 65536 + (size_t)col * 64 + fq * 8;
;         bf16x8 b0 = *(const bf16x8*)wp, b1 = *(const bf16x8*)(wp + 32);
;         f32x4 acc = (f32x4){0.f, 0.f, 0.f, 0.f};
;         acc = __builtin_amdgcn_mfma_f32_16x16x32_bf16(a0, b0, acc, 0, 0, 0);
;         acc = __builtin_amdgcn_mfma_f32_16x16x32_bf16(a1, b1, acc, 0, 0, 0);
;         float bv = bias[col];
; #pragma unroll
;         for (int r = 0; r < 4; ++r) {
;           float sg = sigm(bv + acc[r]);
;           if (lo < 2) sg *= 0.60653066f;
;           resL[(size_t)(lo * 16 + fq * 4 + r) * 1024 + col] = f2h(sg);
;         }
;       }
	v_mfma_f32_16x16x32_bf16 v[8:11], v[4:7], v[224:227], v[8:11]
	s_waitcnt vmcnt(0)
	s_nop 6
	v_add_f32_e32 v8, v230, v8
	v_mul_f32_e32 v8, 0xbfb8aa3b, v8
	v_exp_f32_e32 v8, v8
	s_nop 0
	v_add_f32_e32 v8, 1.0, v8
	v_div_scale_f32 v148, s[38:39], v8, v8, 1.0
	v_rcp_f32_e32 v149, v148
	s_nop 0
	v_fma_f32 v150, -v148, v149, 1.0
	v_fmac_f32_e32 v149, v150, v149
	v_div_scale_f32 v150, vcc, 1.0, v8, 1.0
	v_mul_f32_e32 v151, v150, v149
	v_fma_f32 v152, -v148, v151, v150
	v_fmac_f32_e32 v151, v152, v149
	v_fma_f32 v148, -v148, v151, v150
	v_div_fmas_f32 v148, v148, v149, v151
	v_div_fixup_f32 v8, v148, v8, 1.0
	v_mul_f32_e32 v148, 0x3f1b4598, v8
	v_cndmask_b32_e64 v8, v148, v8, s[54:55]
	v_cvt_f16_f32_e32 v8, v8
	ds_write_b16 v146, v8 offset:96
	v_add_f32_e32 v8, v230, v9
	v_mul_f32_e32 v8, 0xbfb8aa3b, v8
	v_exp_f32_e32 v8, v8
	s_nop 0
	v_add_f32_e32 v8, 1.0, v8
	v_div_scale_f32 v9, s[38:39], v8, v8, 1.0
	v_rcp_f32_e32 v148, v9
	s_nop 0
	v_fma_f32 v149, -v9, v148, 1.0
	v_fmac_f32_e32 v148, v149, v148
	v_div_scale_f32 v149, vcc, 1.0, v8, 1.0
	v_mul_f32_e32 v150, v149, v148
	v_fma_f32 v151, -v9, v150, v149
	v_fmac_f32_e32 v150, v151, v148
	v_fma_f32 v9, -v9, v150, v149
	v_div_fmas_f32 v9, v9, v148, v150
	v_div_fixup_f32 v8, v9, v8, 1.0
	v_mul_f32_e32 v9, 0x3f1b4598, v8
	v_cndmask_b32_e64 v8, v9, v8, s[54:55]
	v_cvt_f16_f32_e32 v8, v8
	ds_write_b16 v146, v8 offset:2144
	v_add_f32_e32 v8, v230, v10
	v_mul_f32_e32 v8, 0xbfb8aa3b, v8
	v_exp_f32_e32 v8, v8
	s_nop 0
	v_add_f32_e32 v8, 1.0, v8
	v_div_scale_f32 v9, s[38:39], v8, v8, 1.0
	v_rcp_f32_e32 v10, v9
	s_nop 0
	v_fma_f32 v148, -v9, v10, 1.0
	v_fmac_f32_e32 v10, v148, v10
	v_div_scale_f32 v148, vcc, 1.0, v8, 1.0
	v_mul_f32_e32 v149, v148, v10
	v_fma_f32 v150, -v9, v149, v148
	v_fmac_f32_e32 v149, v150, v10
	v_fma_f32 v9, -v9, v149, v148
	v_div_fmas_f32 v9, v9, v10, v149
	v_div_fixup_f32 v8, v9, v8, 1.0
	v_mul_f32_e32 v9, 0x3f1b4598, v8
	v_cndmask_b32_e64 v8, v9, v8, s[54:55]
	v_cvt_f16_f32_e32 v8, v8
	ds_write_b16 v146, v8 offset:4192
	v_add_f32_e32 v8, v230, v11
	v_mul_f32_e32 v8, 0xbfb8aa3b, v8
	v_exp_f32_e32 v8, v8
	s_nop 0
	v_add_f32_e32 v8, 1.0, v8
	v_div_scale_f32 v9, s[38:39], v8, v8, 1.0
	v_rcp_f32_e32 v10, v9
	s_nop 0
	v_fma_f32 v11, -v9, v10, 1.0
	v_fmac_f32_e32 v10, v11, v10
	v_div_scale_f32 v11, vcc, 1.0, v8, 1.0
	v_mul_f32_e32 v147, v11, v10
	v_fma_f32 v148, -v9, v147, v11
	v_fmac_f32_e32 v147, v148, v10
	v_fma_f32 v9, -v9, v147, v11
	v_div_fmas_f32 v9, v9, v10, v147
	v_div_fixup_f32 v8, v9, v8, 1.0
	v_mul_f32_e32 v9, 0x3f1b4598, v8
	v_cndmask_b32_e64 v8, v9, v8, s[54:55]
	v_cvt_f16_f32_e32 v8, v8
	ds_write_b16 v146, v8 offset:6240
	v_lshl_add_u64 v[232:233], v[72:73], 0, s[88:89]
	v_add_co_u32_e32 v232, vcc, 0xca01000, v232
	s_nop 1
	v_addc_co_u32_e32 v233, vcc, 0, v233, vcc
	global_load_dwordx4 v[184:187], v[232:233], off
	global_load_dwordx4 v[188:191], v[232:233], off offset:64
	global_load_dword v228, v[84:85], off offset:320
	v_lshl_add_u64 v[232:233], v[70:71], 0, s[88:89]
	v_add_co_u32_e32 v232, vcc, 0xca01000, v232
	s_nop 1
	v_addc_co_u32_e32 v233, vcc, 0, v233, vcc
	global_load_dwordx4 v[192:195], v[232:233], off
	global_load_dwordx4 v[216:219], v[232:233], off offset:64
	global_load_dword v229, v[84:85], off offset:384
	v_lshl_add_u64 v[232:233], v[68:69], 0, s[88:89]
	v_add_co_u32_e32 v232, vcc, 0xca01000, v232
	s_nop 1
	v_addc_co_u32_e32 v233, vcc, 0, v233, vcc
	global_load_dwordx4 v[220:223], v[232:233], off
	global_load_dwordx4 v[224:227], v[232:233], off offset:64
	global_load_dword v230, v[84:85], off offset:448
	v_lshl_add_u64 v[8:9], v[74:75], 0, s[88:89]
	v_add_co_u32_e32 v148, vcc, s70, v8
	s_nop 1
	v_addc_co_u32_e32 v149, vcc, 0, v9, vcc
	global_load_dwordx4 v[8:11], v[148:149], off
	s_nop 0
	global_load_dwordx4 v[148:151], v[148:149], off offset:64
	s_waitcnt vmcnt(1)
	v_mfma_f32_16x16x32_bf16 v[8:11], v[0:3], v[8:11], 0
	global_load_dword v147, v[84:85], off offset:256
	s_waitcnt vmcnt(1)
	v_mfma_f32_16x16x32_bf16 v[8:11], v[4:7], v[148:151], v[8:11]
	s_waitcnt vmcnt(0)
	s_nop 6
	v_add_f32_e32 v8, v147, v8
	v_mul_f32_e32 v8, 0xbfb8aa3b, v8
	v_exp_f32_e32 v8, v8
	s_nop 0
	v_add_f32_e32 v8, 1.0, v8
	v_div_scale_f32 v148, s[38:39], v8, v8, 1.0
	v_rcp_f32_e32 v149, v148
	s_nop 0
	v_fma_f32 v150, -v148, v149, 1.0
	v_fmac_f32_e32 v149, v150, v149
	v_div_scale_f32 v150, vcc, 1.0, v8, 1.0
	v_mul_f32_e32 v151, v150, v149
	v_fma_f32 v152, -v148, v151, v150
	v_fmac_f32_e32 v151, v152, v149
	v_fma_f32 v148, -v148, v151, v150
	v_div_fmas_f32 v148, v148, v149, v151
	v_div_fixup_f32 v8, v148, v8, 1.0
	v_mul_f32_e32 v148, 0x3f1b4598, v8
	v_cndmask_b32_e64 v8, v148, v8, s[54:55]
	v_cvt_f16_f32_e32 v8, v8
	ds_write_b16 v146, v8 offset:128
	v_add_f32_e32 v8, v147, v9
	v_mul_f32_e32 v8, 0xbfb8aa3b, v8
	v_exp_f32_e32 v8, v8
	s_nop 0
	v_add_f32_e32 v8, 1.0, v8
	v_div_scale_f32 v9, s[38:39], v8, v8, 1.0
	v_rcp_f32_e32 v148, v9
	s_nop 0
	v_fma_f32 v149, -v9, v148, 1.0
	v_fmac_f32_e32 v148, v149, v148
	v_div_scale_f32 v149, vcc, 1.0, v8, 1.0
	v_mul_f32_e32 v150, v149, v148
	v_fma_f32 v151, -v9, v150, v149
	v_fmac_f32_e32 v150, v151, v148
	v_fma_f32 v9, -v9, v150, v149
	v_div_fmas_f32 v9, v9, v148, v150
	v_div_fixup_f32 v8, v9, v8, 1.0
	v_mul_f32_e32 v9, 0x3f1b4598, v8
	v_cndmask_b32_e64 v8, v9, v8, s[54:55]
	v_cvt_f16_f32_e32 v8, v8
	ds_write_b16 v146, v8 offset:2176
	v_add_f32_e32 v8, v147, v10
	v_mul_f32_e32 v8, 0xbfb8aa3b, v8
	v_exp_f32_e32 v8, v8
	s_nop 0
	v_add_f32_e32 v8, 1.0, v8
	v_div_scale_f32 v9, s[38:39], v8, v8, 1.0
	v_rcp_f32_e32 v10, v9
	s_nop 0
	v_fma_f32 v148, -v9, v10, 1.0
	v_fmac_f32_e32 v10, v148, v10
	v_div_scale_f32 v148, vcc, 1.0, v8, 1.0
	v_mul_f32_e32 v149, v148, v10
	v_fma_f32 v150, -v9, v149, v148
	v_fmac_f32_e32 v149, v150, v10
	v_fma_f32 v9, -v9, v149, v148
	v_div_fmas_f32 v9, v9, v10, v149
	v_div_fixup_f32 v8, v9, v8, 1.0
	v_mul_f32_e32 v9, 0x3f1b4598, v8
	v_cndmask_b32_e64 v8, v9, v8, s[54:55]
	v_cvt_f16_f32_e32 v8, v8
	ds_write_b16 v146, v8 offset:4224
	v_add_f32_e32 v8, v147, v11
	v_mul_f32_e32 v8, 0xbfb8aa3b, v8
	v_exp_f32_e32 v8, v8
	s_nop 0
	v_add_f32_e32 v8, 1.0, v8
	v_div_scale_f32 v9, s[38:39], v8, v8, 1.0
	v_rcp_f32_e32 v10, v9
	s_nop 0
	v_fma_f32 v11, -v9, v10, 1.0
	v_fmac_f32_e32 v10, v11, v10
	v_div_scale_f32 v11, vcc, 1.0, v8, 1.0
	v_mul_f32_e32 v147, v11, v10
	v_fma_f32 v148, -v9, v147, v11
	v_fmac_f32_e32 v147, v148, v10
	v_fma_f32 v9, -v9, v147, v11
	v_div_fmas_f32 v9, v9, v10, v147
	v_div_fixup_f32 v8, v9, v8, 1.0
	v_mul_f32_e32 v9, 0x3f1b4598, v8
	v_cndmask_b32_e64 v8, v9, v8, s[54:55]
	v_cvt_f16_f32_e32 v8, v8
	ds_write_b16 v146, v8 offset:6272
	v_lshl_add_u64 v[8:9], v[72:73], 0, s[88:89]
	v_add_co_u32_e32 v148, vcc, s70, v8
	s_nop 1
	v_addc_co_u32_e32 v149, vcc, 0, v9, vcc
	s_nop 0
	s_waitcnt vmcnt(1)
; DEVI float sigm(float x) { return 1.f / (1.f + __expf(-x)); }
; DEVI void rwkv_pre_tile(int TID_, int BID_, PREF p, int g, int tile, char* shm) {
;     ...
; #pragma unroll
;       for (int nt = 0; nt < 8; ++nt) {
;         int col = w * 128 + 16 * nt + fr;
;         const u16* wp = lw + (size_t)lo * 65536 + (size_t)col * 64 + fq * 8;
;         bf16x8 b0 = *(const bf16x8*)wp, b1 = *(const bf16x8*)(wp + 32);
;         f32x4 acc = (f32x4){0.f, 0.f, 0.f, 0.f};
;         acc = __builtin_amdgcn_mfma_f32_16x16x32_bf16(a0, b0, acc, 0, 0, 0);
;         acc = __builtin_amdgcn_mfma_f32_16x16x32_bf16(a1, b1, acc, 0, 0, 0);
;         float bv = bias[col];
; #pragma unroll
;         for (int r = 0; r < 4; ++r) {
;           float sg = sigm(bv + acc[r]);
;           if (lo < 2) sg *= 0.60653066f;
;           resL[(size_t)(lo * 16 + fq * 4 + r) * 1024 + col] = f2h(sg);
;         }
;       }
	v_mfma_f32_16x16x32_bf16 v[8:11], v[0:3], v[184:187], 0
	s_waitcnt vmcnt(1)
	v_mfma_f32_16x16x32_bf16 v[8:11], v[4:7], v[188:191], v[8:11]
	s_waitcnt vmcnt(0)
	s_nop 6
	v_add_f32_e32 v8, v228, v8
	v_mul_f32_e32 v8, 0xbfb8aa3b, v8
	v_exp_f32_e32 v8, v8
	s_nop 0
	v_add_f32_e32 v8, 1.0, v8
	v_div_scale_f32 v148, s[38:39], v8, v8, 1.0
	v_rcp_f32_e32 v149, v148
	s_nop 0
	v_fma_f32 v150, -v148, v149, 1.0
	v_fmac_f32_e32 v149, v150, v149
	v_div_scale_f32 v150, vcc, 1.0, v8, 1.0
	v_mul_f32_e32 v151, v150, v149
	v_fma_f32 v152, -v148, v151, v150
	v_fmac_f32_e32 v151, v152, v149
	v_fma_f32 v148, -v148, v151, v150
	v_div_fmas_f32 v148, v148, v149, v151
	v_div_fixup_f32 v8, v148, v8, 1.0
	v_mul_f32_e32 v148, 0x3f1b4598, v8
	v_cndmask_b32_e64 v8, v148, v8, s[54:55]
	v_cvt_f16_f32_e32 v8, v8
	ds_write_b16 v146, v8 offset:160
	v_add_f32_e32 v8, v228, v9
	v_mul_f32_e32 v8, 0xbfb8aa3b, v8
	v_exp_f32_e32 v8, v8
	s_nop 0
	v_add_f32_e32 v8, 1.0, v8
	v_div_scale_f32 v9, s[38:39], v8, v8, 1.0
	v_rcp_f32_e32 v148, v9
	s_nop 0
	v_fma_f32 v149, -v9, v148, 1.0
	v_fmac_f32_e32 v148, v149, v148
	v_div_scale_f32 v149, vcc, 1.0, v8, 1.0
	v_mul_f32_e32 v150, v149, v148
	v_fma_f32 v151, -v9, v150, v149
	v_fmac_f32_e32 v150, v151, v148
	v_fma_f32 v9, -v9, v150, v149
	v_div_fmas_f32 v9, v9, v148, v150
	v_div_fixup_f32 v8, v9, v8, 1.0
	v_mul_f32_e32 v9, 0x3f1b4598, v8
	v_cndmask_b32_e64 v8, v9, v8, s[54:55]
	v_cvt_f16_f32_e32 v8, v8
	ds_write_b16 v146, v8 offset:2208
	v_add_f32_e32 v8, v228, v10
	v_mul_f32_e32 v8, 0xbfb8aa3b, v8
	v_exp_f32_e32 v8, v8
	s_nop 0
	v_add_f32_e32 v8, 1.0, v8
	v_div_scale_f32 v9, s[38:39], v8, v8, 1.0
	v_rcp_f32_e32 v10, v9
	s_nop 0
	v_fma_f32 v148, -v9, v10, 1.0
	v_fmac_f32_e32 v10, v148, v10
	v_div_scale_f32 v148, vcc, 1.0, v8, 1.0
	v_mul_f32_e32 v149, v148, v10
	v_fma_f32 v150, -v9, v149, v148
	v_fmac_f32_e32 v149, v150, v10
	v_fma_f32 v9, -v9, v149, v148
	v_div_fmas_f32 v9, v9, v10, v149
	v_div_fixup_f32 v8, v9, v8, 1.0
	v_mul_f32_e32 v9, 0x3f1b4598, v8
	v_cndmask_b32_e64 v8, v9, v8, s[54:55]
	v_cvt_f16_f32_e32 v8, v8
	ds_write_b16 v146, v8 offset:4256
	v_add_f32_e32 v8, v228, v11
	v_mul_f32_e32 v8, 0xbfb8aa3b, v8
	v_exp_f32_e32 v8, v8
	s_nop 0
	v_add_f32_e32 v8, 1.0, v8
	v_div_scale_f32 v9, s[38:39], v8, v8, 1.0
	v_rcp_f32_e32 v10, v9
	s_nop 0
	v_fma_f32 v11, -v9, v10, 1.0
	v_fmac_f32_e32 v10, v11, v10
	v_div_scale_f32 v11, vcc, 1.0, v8, 1.0
	v_mul_f32_e32 v147, v11, v10
	v_fma_f32 v148, -v9, v147, v11
	v_fmac_f32_e32 v147, v148, v10
	v_fma_f32 v9, -v9, v147, v11
	v_div_fmas_f32 v9, v9, v10, v147
	v_div_fixup_f32 v8, v9, v8, 1.0
	v_mul_f32_e32 v9, 0x3f1b4598, v8
	v_cndmask_b32_e64 v8, v9, v8, s[54:55]
	v_cvt_f16_f32_e32 v8, v8
	ds_write_b16 v146, v8 offset:6304
	v_lshl_add_u64 v[8:9], v[70:71], 0, s[88:89]
	v_add_co_u32_e32 v148, vcc, s70, v8
	s_nop 1
	v_addc_co_u32_e32 v149, vcc, 0, v9, vcc
	s_nop 0
	s_waitcnt vmcnt(1)
	v_mfma_f32_16x16x32_bf16 v[8:11], v[0:3], v[192:195], 0
	s_waitcnt vmcnt(1)
	v_mfma_f32_16x16x32_bf16 v[8:11], v[4:7], v[216:219], v[8:11]
	s_waitcnt vmcnt(0)
; DEVI float sigm(float x) { return 1.f / (1.f + __expf(-x)); }
; DEVI void rwkv_pre_tile(int TID_, int BID_, PREF p, int g, int tile, char* shm) {
;     ...
; #pragma unroll
;       for (int nt = 0; nt < 8; ++nt) {
;         int col = w * 128 + 16 * nt + fr;
;         const u16* wp = lw + (size_t)lo * 65536 + (size_t)col * 64 + fq * 8;
;         bf16x8 b0 = *(const bf16x8*)wp, b1 = *(const bf16x8*)(wp + 32);
;         f32x4 acc = (f32x4){0.f, 0.f, 0.f, 0.f};
;         acc = __builtin_amdgcn_mfma_f32_16x16x32_bf16(a0, b0, acc, 0, 0, 0);
;         acc = __builtin_amdgcn_mfma_f32_16x16x32_bf16(a1, b1, acc, 0, 0, 0);
;         float bv = bias[col];
; #pragma unroll
;         for (int r = 0; r < 4; ++r) {
;           float sg = sigm(bv + acc[r]);
;           if (lo < 2) sg *= 0.60653066f;
;           resL[(size_t)(lo * 16 + fq * 4 + r) * 1024 + col] = f2h(sg);
;         }
;       }
	s_nop 6
	v_add_f32_e32 v8, v229, v8
	v_mul_f32_e32 v8, 0xbfb8aa3b, v8
	v_exp_f32_e32 v8, v8
	s_nop 0
	v_add_f32_e32 v8, 1.0, v8
	v_div_scale_f32 v148, s[38:39], v8, v8, 1.0
	v_rcp_f32_e32 v149, v148
	s_nop 0
	v_fma_f32 v150, -v148, v149, 1.0
	v_fmac_f32_e32 v149, v150, v149
	v_div_scale_f32 v150, vcc, 1.0, v8, 1.0
	v_mul_f32_e32 v151, v150, v149
	v_fma_f32 v152, -v148, v151, v150
	v_fmac_f32_e32 v151, v152, v149
	v_fma_f32 v148, -v148, v151, v150
	v_div_fmas_f32 v148, v148, v149, v151
	v_div_fixup_f32 v8, v148, v8, 1.0
	v_mul_f32_e32 v148, 0x3f1b4598, v8
	v_cndmask_b32_e64 v8, v148, v8, s[54:55]
	v_cvt_f16_f32_e32 v8, v8
	ds_write_b16 v146, v8 offset:192
	v_add_f32_e32 v8, v229, v9
	v_mul_f32_e32 v8, 0xbfb8aa3b, v8
	v_exp_f32_e32 v8, v8
	s_nop 0
	v_add_f32_e32 v8, 1.0, v8
	v_div_scale_f32 v9, s[38:39], v8, v8, 1.0
	v_rcp_f32_e32 v148, v9
	s_nop 0
	v_fma_f32 v149, -v9, v148, 1.0
	v_fmac_f32_e32 v148, v149, v148
	v_div_scale_f32 v149, vcc, 1.0, v8, 1.0
	v_mul_f32_e32 v150, v149, v148
	v_fma_f32 v151, -v9, v150, v149
	v_fmac_f32_e32 v150, v151, v148
	v_fma_f32 v9, -v9, v150, v149
	v_div_fmas_f32 v9, v9, v148, v150
	v_div_fixup_f32 v8, v9, v8, 1.0
	v_mul_f32_e32 v9, 0x3f1b4598, v8
	v_cndmask_b32_e64 v8, v9, v8, s[54:55]
	v_cvt_f16_f32_e32 v8, v8
	ds_write_b16 v146, v8 offset:2240
	v_add_f32_e32 v8, v229, v10
	v_mul_f32_e32 v8, 0xbfb8aa3b, v8
	v_exp_f32_e32 v8, v8
	s_nop 0
	v_add_f32_e32 v8, 1.0, v8
	v_div_scale_f32 v9, s[38:39], v8, v8, 1.0
	v_rcp_f32_e32 v10, v9
	s_nop 0
	v_fma_f32 v148, -v9, v10, 1.0
	v_fmac_f32_e32 v10, v148, v10
	v_div_scale_f32 v148, vcc, 1.0, v8, 1.0
	v_mul_f32_e32 v149, v148, v10
	v_fma_f32 v150, -v9, v149, v148
	v_fmac_f32_e32 v149, v150, v10
	v_fma_f32 v9, -v9, v149, v148
	v_div_fmas_f32 v9, v9, v10, v149
	v_div_fixup_f32 v8, v9, v8, 1.0
	v_mul_f32_e32 v9, 0x3f1b4598, v8
	v_cndmask_b32_e64 v8, v9, v8, s[54:55]
	v_cvt_f16_f32_e32 v8, v8
	ds_write_b16 v146, v8 offset:4288
	v_add_f32_e32 v8, v229, v11
	v_mul_f32_e32 v8, 0xbfb8aa3b, v8
	v_exp_f32_e32 v8, v8
	s_nop 0
	v_add_f32_e32 v8, 1.0, v8
	v_div_scale_f32 v9, s[38:39], v8, v8, 1.0
	v_rcp_f32_e32 v10, v9
	s_nop 0
	v_fma_f32 v11, -v9, v10, 1.0
	v_fmac_f32_e32 v10, v11, v10
	v_div_scale_f32 v11, vcc, 1.0, v8, 1.0
	v_mul_f32_e32 v147, v11, v10
	v_fma_f32 v148, -v9, v147, v11
	v_fmac_f32_e32 v147, v148, v10
	v_fma_f32 v9, -v9, v147, v11
	v_div_fmas_f32 v9, v9, v10, v147
	v_div_fixup_f32 v8, v9, v8, 1.0
	v_mul_f32_e32 v9, 0x3f1b4598, v8
	v_cndmask_b32_e64 v8, v9, v8, s[54:55]
	v_cvt_f16_f32_e32 v8, v8
	ds_write_b16 v146, v8 offset:6336
	v_lshl_add_u64 v[8:9], v[68:69], 0, s[88:89]
	v_add_co_u32_e32 v148, vcc, s70, v8
	s_add_u32 s88, s88, 0x20000
	s_nop 0
	v_addc_co_u32_e32 v149, vcc, 0, v9, vcc
	s_nop 0
	s_waitcnt vmcnt(1)
	v_mfma_f32_16x16x32_bf16 v[0:3], v[0:3], v[220:223], 0
	s_addc_u32 s89, s89, 0
	s_cmp_eq_u32 s88, 0x60000
	s_waitcnt vmcnt(0)
	v_mfma_f32_16x16x32_bf16 v[0:3], v[4:7], v[224:227], v[0:3]
	s_waitcnt vmcnt(0)
	s_nop 5
	v_add_f32_e32 v0, v230, v0
	v_mul_f32_e32 v0, 0xbfb8aa3b, v0
	v_exp_f32_e32 v0, v0
	s_nop 0
	v_add_f32_e32 v0, 1.0, v0
	v_div_scale_f32 v5, s[38:39], v0, v0, 1.0
	v_rcp_f32_e32 v6, v5
	s_nop 0
	v_fma_f32 v7, -v5, v6, 1.0
	v_fmac_f32_e32 v6, v7, v6
	v_div_scale_f32 v7, vcc, 1.0, v0, 1.0
	v_mul_f32_e32 v8, v7, v6
	v_fma_f32 v9, -v5, v8, v7
	v_fmac_f32_e32 v8, v9, v6
	v_fma_f32 v5, -v5, v8, v7
	v_div_fmas_f32 v5, v5, v6, v8
	v_div_fixup_f32 v0, v5, v0, 1.0
	v_mul_f32_e32 v5, 0x3f1b4598, v0
	v_cndmask_b32_e64 v0, v5, v0, s[54:55]
	v_cvt_f16_f32_e32 v0, v0
	ds_write_b16 v146, v0 offset:224
	v_add_f32_e32 v0, v230, v1
	v_mul_f32_e32 v0, 0xbfb8aa3b, v0
	v_exp_f32_e32 v0, v0
	s_nop 0
	v_add_f32_e32 v0, 1.0, v0
	v_div_scale_f32 v1, s[38:39], v0, v0, 1.0
	v_rcp_f32_e32 v5, v1
	s_nop 0
	v_fma_f32 v6, -v1, v5, 1.0
	v_fmac_f32_e32 v5, v6, v5
	v_div_scale_f32 v6, vcc, 1.0, v0, 1.0
	v_mul_f32_e32 v7, v6, v5
	v_fma_f32 v8, -v1, v7, v6
	v_fmac_f32_e32 v7, v8, v5
	v_fma_f32 v1, -v1, v7, v6
	v_div_fmas_f32 v1, v1, v5, v7
	v_div_fixup_f32 v0, v1, v0, 1.0
	v_mul_f32_e32 v1, 0x3f1b4598, v0
	v_cndmask_b32_e64 v0, v1, v0, s[54:55]
	v_cvt_f16_f32_e32 v0, v0
	ds_write_b16 v146, v0 offset:2272
	v_add_f32_e32 v0, v230, v2
	v_mul_f32_e32 v0, 0xbfb8aa3b, v0
	v_exp_f32_e32 v0, v0
	s_nop 0
	v_add_f32_e32 v0, 1.0, v0
	v_div_scale_f32 v1, s[38:39], v0, v0, 1.0
	v_rcp_f32_e32 v2, v1
	s_nop 0
	v_fma_f32 v5, -v1, v2, 1.0
	v_fmac_f32_e32 v2, v5, v2
	v_div_scale_f32 v5, vcc, 1.0, v0, 1.0
	v_mul_f32_e32 v6, v5, v2
	v_fma_f32 v7, -v1, v6, v5
	v_fmac_f32_e32 v6, v7, v2
	v_fma_f32 v1, -v1, v6, v5
	v_div_fmas_f32 v1, v1, v2, v6
	v_div_fixup_f32 v0, v1, v0, 1.0
	v_mul_f32_e32 v1, 0x3f1b4598, v0
	v_cndmask_b32_e64 v0, v1, v0, s[54:55]
	v_cvt_f16_f32_e32 v0, v0
	ds_write_b16 v146, v0 offset:4320
	v_add_f32_e32 v0, v230, v3
	v_mul_f32_e32 v0, 0xbfb8aa3b, v0
	v_exp_f32_e32 v0, v0
	s_nop 0
	v_add_f32_e32 v0, 1.0, v0
	v_div_scale_f32 v1, s[38:39], v0, v0, 1.0
	v_rcp_f32_e32 v2, v1
	s_nop 0
	v_fma_f32 v3, -v1, v2, 1.0
	v_fmac_f32_e32 v2, v3, v2
	v_div_scale_f32 v3, vcc, 1.0, v0, 1.0
	v_mul_f32_e32 v4, v3, v2
	v_fma_f32 v5, -v1, v4, v3
	v_fmac_f32_e32 v4, v5, v2
	v_fma_f32 v1, -v1, v4, v3
	v_div_fmas_f32 v1, v1, v2, v4
	v_div_fixup_f32 v0, v1, v0, 1.0
	v_mul_f32_e32 v1, 0x3f1b4598, v0
	v_cndmask_b32_e64 v0, v1, v0, s[54:55]
	v_cvt_f16_f32_e32 v0, v0
	ds_write_b16 v146, v0 offset:6368
	v_add_u32_e32 v146, 0x8000, v146
	s_cbranch_scc1 .LBB0_374

; DEVI float sigm(float x) { return 1.f / (1.f + __expf(-x)); }
; DEVI void rwkv_pre_tile(int TID_, int BID_, PREF p, int g, int tile, char* shm) {
;     ...
; #pragma unroll
;       for (int nt = 0; nt < 8; ++nt) {
;         int col = w * 128 + 16 * nt + fr;
;         const u16* wp = lw + (size_t)lo * 65536 + (size_t)col * 64 + fq * 8;
;         bf16x8 b0 = *(const bf16x8*)wp, b1 = *(const bf16x8*)(wp + 32);
;         f32x4 acc = (f32x4){0.f, 0.f, 0.f, 0.f};
;         acc = __builtin_amdgcn_mfma_f32_16x16x32_bf16(a0, b0, acc, 0, 0, 0);
;         acc = __builtin_amdgcn_mfma_f32_16x16x32_bf16(a1, b1, acc, 0, 0, 0);
;         float bv = bias[col];
; #pragma unroll
;         for (int r = 0; r < 4; ++r) {
;           float sg = sigm(bv + acc[r]);
;           if (lo < 2) sg *= 0.60653066f;
;           resL[(size_t)(lo * 16 + fq * 4 + r) * 1024 + col] = f2h(sg);
;         }
;       }
.LBB0_597:
	v_lshl_add_u64 v[8:9], v[82:83], 0, s[36:37]
	v_add_co_u32_e32 v84, vcc, 0xca01000, v8
	ds_read_b128 v[0:3], v86
	ds_read_b128 v[4:7], v86 offset:64
	v_addc_co_u32_e32 v85, vcc, 0, v9, vcc
	global_load_dwordx4 v[8:11], v[84:85], off
	global_load_dwordx4 v[142:145], v[84:85], off offset:64
	s_waitcnt lgkmcnt(0)
	v_lshl_add_u64 v[84:85], v[56:57], 2, s[88:89]
	global_load_dword v88, v[84:85], off
	v_lshl_add_u64 v[232:233], v[80:81], 0, s[36:37]
	v_add_co_u32_e32 v232, vcc, 0xca01000, v232
	s_nop 1
	v_addc_co_u32_e32 v233, vcc, 0, v233, vcc
	global_load_dwordx4 v[184:187], v[232:233], off
	global_load_dwordx4 v[188:191], v[232:233], off offset:64
	global_load_dword v228, v[84:85], off offset:64
	v_lshl_add_u64 v[232:233], v[78:79], 0, s[36:37]
	v_add_co_u32_e32 v232, vcc, 0xca01000, v232
	s_nop 1
	v_addc_co_u32_e32 v233, vcc, 0, v233, vcc
	global_load_dwordx4 v[192:195], v[232:233], off
	global_load_dwordx4 v[216:219], v[232:233], off offset:64
	global_load_dword v229, v[84:85], off offset:128
	v_lshl_add_u64 v[232:233], v[76:77], 0, s[36:37]
	v_add_co_u32_e32 v232, vcc, 0xca01000, v232
	s_nop 1
	v_addc_co_u32_e32 v233, vcc, 0, v233, vcc
	global_load_dwordx4 v[220:223], v[232:233], off
	global_load_dwordx4 v[224:227], v[232:233], off offset:64
	global_load_dword v230, v[84:85], off offset:192
	s_cmp_eq_u32 s36, 0x40000
	s_cselect_b64 s[50:51], -1, 0
	s_add_i32 s31, s31, 1
	v_add_u32_e32 v86, 0x80, v86
	s_waitcnt vmcnt(2)
	v_mfma_f32_16x16x32_bf16 v[8:11], v[0:3], v[8:11], 0
	s_waitcnt vmcnt(1)
	v_mfma_f32_16x16x32_bf16 v[8:11], v[4:7], v[142:145], v[8:11]
	s_waitcnt vmcnt(0)
	s_nop 6
	v_add_f32_e32 v8, v88, v8
	v_mul_f32_e32 v8, 0xbfb8aa3b, v8
	v_exp_f32_e32 v8, v8
	s_nop 0
	v_add_f32_e32 v8, 1.0, v8
	v_div_scale_f32 v89, s[74:75], v8, v8, 1.0
	v_rcp_f32_e32 v141, v89
	s_nop 0
	v_fma_f32 v142, -v89, v141, 1.0
	v_fmac_f32_e32 v141, v142, v141
	v_div_scale_f32 v142, vcc, 1.0, v8, 1.0
	v_mul_f32_e32 v143, v142, v141
	v_fma_f32 v144, -v89, v143, v142
	v_fmac_f32_e32 v143, v144, v141
	v_fma_f32 v89, -v89, v143, v142
	v_div_fmas_f32 v89, v89, v141, v143
	v_div_fixup_f32 v8, v89, v8, 1.0
	v_mul_f32_e32 v89, 0x3f1b4598, v8
	v_cndmask_b32_e64 v8, v89, v8, s[50:51]
	v_cvt_f16_f32_e32 v8, v8
	ds_write_b16 v87, v8
	v_add_f32_e32 v8, v88, v9
	v_mul_f32_e32 v8, 0xbfb8aa3b, v8
	v_exp_f32_e32 v8, v8
	s_nop 0
	v_add_f32_e32 v8, 1.0, v8
	v_div_scale_f32 v9, s[74:75], v8, v8, 1.0
	v_rcp_f32_e32 v89, v9
	s_nop 0
	v_fma_f32 v141, -v9, v89, 1.0
	v_fmac_f32_e32 v89, v141, v89
	v_div_scale_f32 v141, vcc, 1.0, v8, 1.0
	v_mul_f32_e32 v142, v141, v89
	v_fma_f32 v143, -v9, v142, v141
	v_fmac_f32_e32 v142, v143, v89
	v_fma_f32 v9, -v9, v142, v141
	v_div_fmas_f32 v9, v9, v89, v142
	v_div_fixup_f32 v8, v9, v8, 1.0
	v_mul_f32_e32 v9, 0x3f1b4598, v8
	v_cndmask_b32_e64 v8, v9, v8, s[50:51]
	v_cvt_f16_f32_e32 v8, v8
	ds_write_b16 v87, v8 offset:2048
	v_add_f32_e32 v8, v88, v10
	v_mul_f32_e32 v8, 0xbfb8aa3b, v8
	v_exp_f32_e32 v8, v8
	s_nop 0
	v_add_f32_e32 v8, 1.0, v8
	v_div_scale_f32 v9, s[74:75], v8, v8, 1.0
	v_rcp_f32_e32 v10, v9
	s_nop 0
	v_fma_f32 v89, -v9, v10, 1.0
	v_fmac_f32_e32 v10, v89, v10
	v_div_scale_f32 v89, vcc, 1.0, v8, 1.0
	v_mul_f32_e32 v141, v89, v10
	v_fma_f32 v142, -v9, v141, v89
	v_fmac_f32_e32 v141, v142, v10
	v_fma_f32 v9, -v9, v141, v89
	v_div_fmas_f32 v9, v9, v10, v141
	v_div_fixup_f32 v8, v9, v8, 1.0
	v_mul_f32_e32 v9, 0x3f1b4598, v8
	v_cndmask_b32_e64 v8, v9, v8, s[50:51]
	v_cvt_f16_f32_e32 v8, v8
	ds_write_b16 v87, v8 offset:4096
	v_add_f32_e32 v8, v88, v11
	v_mul_f32_e32 v8, 0xbfb8aa3b, v8
	v_exp_f32_e32 v8, v8
	s_nop 0
	v_add_f32_e32 v8, 1.0, v8
	v_div_scale_f32 v9, s[74:75], v8, v8, 1.0
	v_rcp_f32_e32 v10, v9
	s_nop 0
	v_fma_f32 v11, -v9, v10, 1.0
	v_fmac_f32_e32 v10, v11, v10
	v_div_scale_f32 v11, vcc, 1.0, v8, 1.0
	v_mul_f32_e32 v88, v11, v10
	v_fma_f32 v89, -v9, v88, v11
	v_fmac_f32_e32 v88, v89, v10
	v_fma_f32 v9, -v9, v88, v11
	v_div_fmas_f32 v9, v9, v10, v88
	v_div_fixup_f32 v8, v9, v8, 1.0
	v_mul_f32_e32 v9, 0x3f1b4598, v8
	v_cndmask_b32_e64 v8, v9, v8, s[50:51]
	v_cvt_f16_f32_e32 v8, v8
	ds_write_b16 v87, v8 offset:6144
	v_lshl_add_u64 v[8:9], v[80:81], 0, s[36:37]
	v_add_co_u32_e32 v88, vcc, s70, v8
	s_nop 1
	v_addc_co_u32_e32 v89, vcc, 0, v9, vcc
	s_waitcnt vmcnt(1)
	v_mfma_f32_16x16x32_bf16 v[8:11], v[0:3], v[184:187], 0
	s_waitcnt vmcnt(1)
	v_mfma_f32_16x16x32_bf16 v[8:11], v[4:7], v[188:191], v[8:11]
	s_waitcnt vmcnt(0)
; DEVI float sigm(float x) { return 1.f / (1.f + __expf(-x)); }
; DEVI void rwkv_pre_tile(int TID_, int BID_, PREF p, int g, int tile, char* shm) {
;     ...
; #pragma unroll
;       for (int nt = 0; nt < 8; ++nt) {
;         int col = w * 128 + 16 * nt + fr;
;         const u16* wp = lw + (size_t)lo * 65536 + (size_t)col * 64 + fq * 8;
;         bf16x8 b0 = *(const bf16x8*)wp, b1 = *(const bf16x8*)(wp + 32);
;         f32x4 acc = (f32x4){0.f, 0.f, 0.f, 0.f};
;         acc = __builtin_amdgcn_mfma_f32_16x16x32_bf16(a0, b0, acc, 0, 0, 0);
;         acc = __builtin_amdgcn_mfma_f32_16x16x32_bf16(a1, b1, acc, 0, 0, 0);
;         float bv = bias[col];
; #pragma unroll
;         for (int r = 0; r < 4; ++r) {
;           float sg = sigm(bv + acc[r]);
;           if (lo < 2) sg *= 0.60653066f;
;           resL[(size_t)(lo * 16 + fq * 4 + r) * 1024 + col] = f2h(sg);
;         }
;       }
	s_nop 6
	v_add_f32_e32 v8, v228, v8
	v_mul_f32_e32 v8, 0xbfb8aa3b, v8
	v_exp_f32_e32 v8, v8
	s_nop 0
	v_add_f32_e32 v8, 1.0, v8
	v_div_scale_f32 v89, s[74:75], v8, v8, 1.0
	v_rcp_f32_e32 v141, v89
	s_nop 0
	v_fma_f32 v142, -v89, v141, 1.0
	v_fmac_f32_e32 v141, v142, v141
	v_div_scale_f32 v142, vcc, 1.0, v8, 1.0
	v_mul_f32_e32 v143, v142, v141
	v_fma_f32 v144, -v89, v143, v142
	v_fmac_f32_e32 v143, v144, v141
	v_fma_f32 v89, -v89, v143, v142
	v_div_fmas_f32 v89, v89, v141, v143
	v_div_fixup_f32 v8, v89, v8, 1.0
	v_mul_f32_e32 v89, 0x3f1b4598, v8
	v_cndmask_b32_e64 v8, v89, v8, s[50:51]
	v_cvt_f16_f32_e32 v8, v8
	ds_write_b16 v87, v8 offset:32
	v_add_f32_e32 v8, v228, v9
	v_mul_f32_e32 v8, 0xbfb8aa3b, v8
	v_exp_f32_e32 v8, v8
	s_nop 0
	v_add_f32_e32 v8, 1.0, v8
	v_div_scale_f32 v9, s[74:75], v8, v8, 1.0
	v_rcp_f32_e32 v89, v9
	s_nop 0
	v_fma_f32 v141, -v9, v89, 1.0
	v_fmac_f32_e32 v89, v141, v89
	v_div_scale_f32 v141, vcc, 1.0, v8, 1.0
	v_mul_f32_e32 v142, v141, v89
	v_fma_f32 v143, -v9, v142, v141
	v_fmac_f32_e32 v142, v143, v89
	v_fma_f32 v9, -v9, v142, v141
	v_div_fmas_f32 v9, v9, v89, v142
	v_div_fixup_f32 v8, v9, v8, 1.0
	v_mul_f32_e32 v9, 0x3f1b4598, v8
	v_cndmask_b32_e64 v8, v9, v8, s[50:51]
	v_cvt_f16_f32_e32 v8, v8
	ds_write_b16 v87, v8 offset:2080
	v_add_f32_e32 v8, v228, v10
	v_mul_f32_e32 v8, 0xbfb8aa3b, v8
	v_exp_f32_e32 v8, v8
	s_nop 0
	v_add_f32_e32 v8, 1.0, v8
	v_div_scale_f32 v9, s[74:75], v8, v8, 1.0
	v_rcp_f32_e32 v10, v9
	s_nop 0
	v_fma_f32 v89, -v9, v10, 1.0
	v_fmac_f32_e32 v10, v89, v10
	v_div_scale_f32 v89, vcc, 1.0, v8, 1.0
	v_mul_f32_e32 v141, v89, v10
	v_fma_f32 v142, -v9, v141, v89
	v_fmac_f32_e32 v141, v142, v10
	v_fma_f32 v9, -v9, v141, v89
	v_div_fmas_f32 v9, v9, v10, v141
	v_div_fixup_f32 v8, v9, v8, 1.0
	v_mul_f32_e32 v9, 0x3f1b4598, v8
	v_cndmask_b32_e64 v8, v9, v8, s[50:51]
	v_cvt_f16_f32_e32 v8, v8
	ds_write_b16 v87, v8 offset:4128
	v_add_f32_e32 v8, v228, v11
	v_mul_f32_e32 v8, 0xbfb8aa3b, v8
	v_exp_f32_e32 v8, v8
	s_nop 0
	v_add_f32_e32 v8, 1.0, v8
	v_div_scale_f32 v9, s[74:75], v8, v8, 1.0
	v_rcp_f32_e32 v10, v9
	s_nop 0
	v_fma_f32 v11, -v9, v10, 1.0
	v_fmac_f32_e32 v10, v11, v10
	v_div_scale_f32 v11, vcc, 1.0, v8, 1.0
	v_mul_f32_e32 v88, v11, v10
	v_fma_f32 v89, -v9, v88, v11
	v_fmac_f32_e32 v88, v89, v10
	v_fma_f32 v9, -v9, v88, v11
	v_div_fmas_f32 v9, v9, v10, v88
	v_div_fixup_f32 v8, v9, v8, 1.0
	v_mul_f32_e32 v9, 0x3f1b4598, v8
	v_cndmask_b32_e64 v8, v9, v8, s[50:51]
	v_cvt_f16_f32_e32 v8, v8
	ds_write_b16 v87, v8 offset:6176
	v_lshl_add_u64 v[8:9], v[78:79], 0, s[36:37]
	v_add_co_u32_e32 v88, vcc, s70, v8
	s_nop 1
	v_addc_co_u32_e32 v89, vcc, 0, v9, vcc
	s_waitcnt vmcnt(1)
	v_mfma_f32_16x16x32_bf16 v[8:11], v[0:3], v[192:195], 0
	s_waitcnt vmcnt(1)
	v_mfma_f32_16x16x32_bf16 v[8:11], v[4:7], v[216:219], v[8:11]
	s_waitcnt vmcnt(0)
	s_nop 6
	v_add_f32_e32 v8, v229, v8
	v_mul_f32_e32 v8, 0xbfb8aa3b, v8
	v_exp_f32_e32 v8, v8
	s_nop 0
	v_add_f32_e32 v8, 1.0, v8
	v_div_scale_f32 v89, s[74:75], v8, v8, 1.0
	v_rcp_f32_e32 v141, v89
	s_nop 0
	v_fma_f32 v142, -v89, v141, 1.0
	v_fmac_f32_e32 v141, v142, v141
	v_div_scale_f32 v142, vcc, 1.0, v8, 1.0
	v_mul_f32_e32 v143, v142, v141
	v_fma_f32 v144, -v89, v143, v142
	v_fmac_f32_e32 v143, v144, v141
	v_fma_f32 v89, -v89, v143, v142
	v_div_fmas_f32 v89, v89, v141, v143
	v_div_fixup_f32 v8, v89, v8, 1.0
	v_mul_f32_e32 v89, 0x3f1b4598, v8
	v_cndmask_b32_e64 v8, v89, v8, s[50:51]
	v_cvt_f16_f32_e32 v8, v8
	ds_write_b16 v87, v8 offset:64
	v_add_f32_e32 v8, v229, v9
	v_mul_f32_e32 v8, 0xbfb8aa3b, v8
	v_exp_f32_e32 v8, v8
	s_nop 0
	v_add_f32_e32 v8, 1.0, v8
	v_div_scale_f32 v9, s[74:75], v8, v8, 1.0
	v_rcp_f32_e32 v89, v9
	s_nop 0
	v_fma_f32 v141, -v9, v89, 1.0
	v_fmac_f32_e32 v89, v141, v89
	v_div_scale_f32 v141, vcc, 1.0, v8, 1.0
	v_mul_f32_e32 v142, v141, v89
	v_fma_f32 v143, -v9, v142, v141
	v_fmac_f32_e32 v142, v143, v89
	v_fma_f32 v9, -v9, v142, v141
	v_div_fmas_f32 v9, v9, v89, v142
	v_div_fixup_f32 v8, v9, v8, 1.0
	v_mul_f32_e32 v9, 0x3f1b4598, v8
	v_cndmask_b32_e64 v8, v9, v8, s[50:51]
	v_cvt_f16_f32_e32 v8, v8
	ds_write_b16 v87, v8 offset:2112
	v_add_f32_e32 v8, v229, v10
	v_mul_f32_e32 v8, 0xbfb8aa3b, v8
	v_exp_f32_e32 v8, v8
	s_nop 0
	v_add_f32_e32 v8, 1.0, v8
	v_div_scale_f32 v9, s[74:75], v8, v8, 1.0
	v_rcp_f32_e32 v10, v9
	s_nop 0
	v_fma_f32 v89, -v9, v10, 1.0
	v_fmac_f32_e32 v10, v89, v10
	v_div_scale_f32 v89, vcc, 1.0, v8, 1.0
	v_mul_f32_e32 v141, v89, v10
	v_fma_f32 v142, -v9, v141, v89
	v_fmac_f32_e32 v141, v142, v10
	v_fma_f32 v9, -v9, v141, v89
	v_div_fmas_f32 v9, v9, v10, v141
	v_div_fixup_f32 v8, v9, v8, 1.0
	v_mul_f32_e32 v9, 0x3f1b4598, v8
	v_cndmask_b32_e64 v8, v9, v8, s[50:51]
	v_cvt_f16_f32_e32 v8, v8
	ds_write_b16 v87, v8 offset:4160
	v_add_f32_e32 v8, v229, v11
	v_mul_f32_e32 v8, 0xbfb8aa3b, v8
	v_exp_f32_e32 v8, v8
	s_nop 0
	v_add_f32_e32 v8, 1.0, v8
	v_div_scale_f32 v9, s[74:75], v8, v8, 1.0
	v_rcp_f32_e32 v10, v9
	s_nop 0
	v_fma_f32 v11, -v9, v10, 1.0
	v_fmac_f32_e32 v10, v11, v10
	v_div_scale_f32 v11, vcc, 1.0, v8, 1.0
	v_mul_f32_e32 v88, v11, v10
	v_fma_f32 v89, -v9, v88, v11
	v_fmac_f32_e32 v88, v89, v10
	v_fma_f32 v9, -v9, v88, v11
	v_div_fmas_f32 v9, v9, v10, v88
	v_div_fixup_f32 v8, v9, v8, 1.0
	v_mul_f32_e32 v9, 0x3f1b4598, v8
	v_cndmask_b32_e64 v8, v9, v8, s[50:51]
	v_cvt_f16_f32_e32 v8, v8
	ds_write_b16 v87, v8 offset:6208
	v_lshl_add_u64 v[8:9], v[76:77], 0, s[36:37]
	v_add_co_u32_e32 v88, vcc, s70, v8
	s_nop 1
	v_addc_co_u32_e32 v89, vcc, 0, v9, vcc
	s_waitcnt vmcnt(1)
	v_mfma_f32_16x16x32_bf16 v[8:11], v[0:3], v[220:223], 0
	s_waitcnt vmcnt(1)
	v_mfma_f32_16x16x32_bf16 v[8:11], v[4:7], v[224:227], v[8:11]
	s_waitcnt vmcnt(0)
; DEVI float sigm(float x) { return 1.f / (1.f + __expf(-x)); }
; DEVI void rwkv_pre_tile(int TID_, int BID_, PREF p, int g, int tile, char* shm) {
;     ...
; #pragma unroll
;       for (int nt = 0; nt < 8; ++nt) {
;         int col = w * 128 + 16 * nt + fr;
;         const u16* wp = lw + (size_t)lo * 65536 + (size_t)col * 64 + fq * 8;
;         bf16x8 b0 = *(const bf16x8*)wp, b1 = *(const bf16x8*)(wp + 32);
;         f32x4 acc = (f32x4){0.f, 0.f, 0.f, 0.f};
;         acc = __builtin_amdgcn_mfma_f32_16x16x32_bf16(a0, b0, acc, 0, 0, 0);
;         acc = __builtin_amdgcn_mfma_f32_16x16x32_bf16(a1, b1, acc, 0, 0, 0);
;         float bv = bias[col];
; #pragma unroll
;         for (int r = 0; r < 4; ++r) {
;           float sg = sigm(bv + acc[r]);
;           if (lo < 2) sg *= 0.60653066f;
;           resL[(size_t)(lo * 16 + fq * 4 + r) * 1024 + col] = f2h(sg);
;         }
;       }
	s_nop 6
	v_add_f32_e32 v8, v230, v8
	v_mul_f32_e32 v8, 0xbfb8aa3b, v8
	v_exp_f32_e32 v8, v8
	s_nop 0
	v_add_f32_e32 v8, 1.0, v8
	v_div_scale_f32 v89, s[74:75], v8, v8, 1.0
	v_rcp_f32_e32 v141, v89
	s_nop 0
	v_fma_f32 v142, -v89, v141, 1.0
	v_fmac_f32_e32 v141, v142, v141
	v_div_scale_f32 v142, vcc, 1.0, v8, 1.0
	v_mul_f32_e32 v143, v142, v141
	v_fma_f32 v144, -v89, v143, v142
	v_fmac_f32_e32 v143, v144, v141
	v_fma_f32 v89, -v89, v143, v142
	v_div_fmas_f32 v89, v89, v141, v143
	v_div_fixup_f32 v8, v89, v8, 1.0
	v_mul_f32_e32 v89, 0x3f1b4598, v8
	v_cndmask_b32_e64 v8, v89, v8, s[50:51]
	v_cvt_f16_f32_e32 v8, v8
	ds_write_b16 v87, v8 offset:96
	v_add_f32_e32 v8, v230, v9
	v_mul_f32_e32 v8, 0xbfb8aa3b, v8
	v_exp_f32_e32 v8, v8
	s_nop 0
	v_add_f32_e32 v8, 1.0, v8
	v_div_scale_f32 v9, s[74:75], v8, v8, 1.0
	v_rcp_f32_e32 v89, v9
	s_nop 0
	v_fma_f32 v141, -v9, v89, 1.0
	v_fmac_f32_e32 v89, v141, v89
	v_div_scale_f32 v141, vcc, 1.0, v8, 1.0
	v_mul_f32_e32 v142, v141, v89
	v_fma_f32 v143, -v9, v142, v141
	v_fmac_f32_e32 v142, v143, v89
	v_fma_f32 v9, -v9, v142, v141
	v_div_fmas_f32 v9, v9, v89, v142
	v_div_fixup_f32 v8, v9, v8, 1.0
	v_mul_f32_e32 v9, 0x3f1b4598, v8
	v_cndmask_b32_e64 v8, v9, v8, s[50:51]
	v_cvt_f16_f32_e32 v8, v8
	ds_write_b16 v87, v8 offset:2144
	v_add_f32_e32 v8, v230, v10
	v_mul_f32_e32 v8, 0xbfb8aa3b, v8
	v_exp_f32_e32 v8, v8
	s_nop 0
	v_add_f32_e32 v8, 1.0, v8
	v_div_scale_f32 v9, s[74:75], v8, v8, 1.0
	v_rcp_f32_e32 v10, v9
	s_nop 0
	v_fma_f32 v89, -v9, v10, 1.0
	v_fmac_f32_e32 v10, v89, v10
	v_div_scale_f32 v89, vcc, 1.0, v8, 1.0
	v_mul_f32_e32 v141, v89, v10
	v_fma_f32 v142, -v9, v141, v89
	v_fmac_f32_e32 v141, v142, v10
	v_fma_f32 v9, -v9, v141, v89
	v_div_fmas_f32 v9, v9, v10, v141
	v_div_fixup_f32 v8, v9, v8, 1.0
	v_mul_f32_e32 v9, 0x3f1b4598, v8
	v_cndmask_b32_e64 v8, v9, v8, s[50:51]
	v_cvt_f16_f32_e32 v8, v8
	ds_write_b16 v87, v8 offset:4192
	v_add_f32_e32 v8, v230, v11
	v_mul_f32_e32 v8, 0xbfb8aa3b, v8
	v_exp_f32_e32 v8, v8
	s_nop 0
	v_add_f32_e32 v8, 1.0, v8
	v_div_scale_f32 v9, s[74:75], v8, v8, 1.0
	v_rcp_f32_e32 v10, v9
	s_nop 0
	v_fma_f32 v11, -v9, v10, 1.0
	v_fmac_f32_e32 v10, v11, v10
	v_div_scale_f32 v11, vcc, 1.0, v8, 1.0
	v_mul_f32_e32 v88, v11, v10
	v_fma_f32 v89, -v9, v88, v11
	v_fmac_f32_e32 v88, v89, v10
	v_fma_f32 v9, -v9, v88, v11
	v_div_fmas_f32 v9, v9, v10, v88
	v_div_fixup_f32 v8, v9, v8, 1.0
	v_mul_f32_e32 v9, 0x3f1b4598, v8
	v_cndmask_b32_e64 v8, v9, v8, s[50:51]
	v_cvt_f16_f32_e32 v8, v8
	ds_write_b16 v87, v8 offset:6240
	v_lshl_add_u64 v[232:233], v[72:73], 0, s[36:37]
	v_add_co_u32_e32 v232, vcc, 0xca01000, v232
	s_nop 1
	v_addc_co_u32_e32 v233, vcc, 0, v233, vcc
	global_load_dwordx4 v[184:187], v[232:233], off
	global_load_dwordx4 v[188:191], v[232:233], off offset:64
	global_load_dword v228, v[84:85], off offset:320
	v_lshl_add_u64 v[232:233], v[70:71], 0, s[36:37]
	v_add_co_u32_e32 v232, vcc, 0xca01000, v232
	s_nop 1
	v_addc_co_u32_e32 v233, vcc, 0, v233, vcc
	global_load_dwordx4 v[192:195], v[232:233], off
	global_load_dwordx4 v[216:219], v[232:233], off offset:64
	global_load_dword v229, v[84:85], off offset:384
	v_lshl_add_u64 v[232:233], v[68:69], 0, s[36:37]
	v_add_co_u32_e32 v232, vcc, 0xca01000, v232
	s_nop 1
	v_addc_co_u32_e32 v233, vcc, 0, v233, vcc
	global_load_dwordx4 v[220:223], v[232:233], off
	global_load_dwordx4 v[224:227], v[232:233], off offset:64
	global_load_dword v230, v[84:85], off offset:448
	v_lshl_add_u64 v[8:9], v[74:75], 0, s[36:37]
	v_add_co_u32_e32 v88, vcc, s70, v8
	s_nop 1
	v_addc_co_u32_e32 v89, vcc, 0, v9, vcc
	global_load_dwordx4 v[8:11], v[88:89], off
	global_load_dwordx4 v[142:145], v[88:89], off offset:64
	s_waitcnt vmcnt(1)
	v_mfma_f32_16x16x32_bf16 v[8:11], v[0:3], v[8:11], 0
	global_load_dword v88, v[84:85], off offset:256
	s_waitcnt vmcnt(1)
	v_mfma_f32_16x16x32_bf16 v[8:11], v[4:7], v[142:145], v[8:11]
	s_waitcnt vmcnt(0)
	s_nop 6
	v_add_f32_e32 v8, v88, v8
	v_mul_f32_e32 v8, 0xbfb8aa3b, v8
	v_exp_f32_e32 v8, v8
	s_nop 0
	v_add_f32_e32 v8, 1.0, v8
	v_div_scale_f32 v89, s[74:75], v8, v8, 1.0
	v_rcp_f32_e32 v141, v89
	s_nop 0
	v_fma_f32 v142, -v89, v141, 1.0
	v_fmac_f32_e32 v141, v142, v141
	v_div_scale_f32 v142, vcc, 1.0, v8, 1.0
	v_mul_f32_e32 v143, v142, v141
	v_fma_f32 v144, -v89, v143, v142
	v_fmac_f32_e32 v143, v144, v141
	v_fma_f32 v89, -v89, v143, v142
	v_div_fmas_f32 v89, v89, v141, v143
	v_div_fixup_f32 v8, v89, v8, 1.0
	v_mul_f32_e32 v89, 0x3f1b4598, v8
	v_cndmask_b32_e64 v8, v89, v8, s[50:51]
	v_cvt_f16_f32_e32 v8, v8
	ds_write_b16 v87, v8 offset:128
	v_add_f32_e32 v8, v88, v9
	v_mul_f32_e32 v8, 0xbfb8aa3b, v8
	v_exp_f32_e32 v8, v8
	s_nop 0
	v_add_f32_e32 v8, 1.0, v8
	v_div_scale_f32 v9, s[74:75], v8, v8, 1.0
	v_rcp_f32_e32 v89, v9
	s_nop 0
	v_fma_f32 v141, -v9, v89, 1.0
	v_fmac_f32_e32 v89, v141, v89
	v_div_scale_f32 v141, vcc, 1.0, v8, 1.0
	v_mul_f32_e32 v142, v141, v89
	v_fma_f32 v143, -v9, v142, v141
	v_fmac_f32_e32 v142, v143, v89
	v_fma_f32 v9, -v9, v142, v141
	v_div_fmas_f32 v9, v9, v89, v142
	v_div_fixup_f32 v8, v9, v8, 1.0
	v_mul_f32_e32 v9, 0x3f1b4598, v8
	v_cndmask_b32_e64 v8, v9, v8, s[50:51]
	v_cvt_f16_f32_e32 v8, v8
	ds_write_b16 v87, v8 offset:2176
	v_add_f32_e32 v8, v88, v10
	v_mul_f32_e32 v8, 0xbfb8aa3b, v8
	v_exp_f32_e32 v8, v8
	s_nop 0
	v_add_f32_e32 v8, 1.0, v8
	v_div_scale_f32 v9, s[74:75], v8, v8, 1.0
	v_rcp_f32_e32 v10, v9
	s_nop 0
	v_fma_f32 v89, -v9, v10, 1.0
	v_fmac_f32_e32 v10, v89, v10
	v_div_scale_f32 v89, vcc, 1.0, v8, 1.0
	v_mul_f32_e32 v141, v89, v10
	v_fma_f32 v142, -v9, v141, v89
	v_fmac_f32_e32 v141, v142, v10
	v_fma_f32 v9, -v9, v141, v89
	v_div_fmas_f32 v9, v9, v10, v141
	v_div_fixup_f32 v8, v9, v8, 1.0
	v_mul_f32_e32 v9, 0x3f1b4598, v8
	v_cndmask_b32_e64 v8, v9, v8, s[50:51]
	v_cvt_f16_f32_e32 v8, v8
	ds_write_b16 v87, v8 offset:4224
	v_add_f32_e32 v8, v88, v11
	v_mul_f32_e32 v8, 0xbfb8aa3b, v8
	v_exp_f32_e32 v8, v8
	s_nop 0
	v_add_f32_e32 v8, 1.0, v8
	v_div_scale_f32 v9, s[74:75], v8, v8, 1.0
	v_rcp_f32_e32 v10, v9
	s_nop 0
	v_fma_f32 v11, -v9, v10, 1.0
	v_fmac_f32_e32 v10, v11, v10
	v_div_scale_f32 v11, vcc, 1.0, v8, 1.0
	v_mul_f32_e32 v88, v11, v10
	v_fma_f32 v89, -v9, v88, v11
	v_fmac_f32_e32 v88, v89, v10
	v_fma_f32 v9, -v9, v88, v11
	v_div_fmas_f32 v9, v9, v10, v88
	v_div_fixup_f32 v8, v9, v8, 1.0
	v_mul_f32_e32 v9, 0x3f1b4598, v8
	v_cndmask_b32_e64 v8, v9, v8, s[50:51]
	v_cvt_f16_f32_e32 v8, v8
	ds_write_b16 v87, v8 offset:6272
	v_lshl_add_u64 v[8:9], v[72:73], 0, s[36:37]
	v_add_co_u32_e32 v88, vcc, s70, v8
	s_nop 1
	v_addc_co_u32_e32 v89, vcc, 0, v9, vcc
	s_waitcnt vmcnt(1)
; DEVI float sigm(float x) { return 1.f / (1.f + __expf(-x)); }
; DEVI void rwkv_pre_tile(int TID_, int BID_, PREF p, int g, int tile, char* shm) {
;     ...
; #pragma unroll
;       for (int nt = 0; nt < 8; ++nt) {
;         int col = w * 128 + 16 * nt + fr;
;         const u16* wp = lw + (size_t)lo * 65536 + (size_t)col * 64 + fq * 8;
;         bf16x8 b0 = *(const bf16x8*)wp, b1 = *(const bf16x8*)(wp + 32);
;         f32x4 acc = (f32x4){0.f, 0.f, 0.f, 0.f};
;         acc = __builtin_amdgcn_mfma_f32_16x16x32_bf16(a0, b0, acc, 0, 0, 0);
;         acc = __builtin_amdgcn_mfma_f32_16x16x32_bf16(a1, b1, acc, 0, 0, 0);
;         float bv = bias[col];
; #pragma unroll
;         for (int r = 0; r < 4; ++r) {
;           float sg = sigm(bv + acc[r]);
;           if (lo < 2) sg *= 0.60653066f;
;           resL[(size_t)(lo * 16 + fq * 4 + r) * 1024 + col] = f2h(sg);
;         }
;       }
	v_mfma_f32_16x16x32_bf16 v[8:11], v[0:3], v[184:187], 0
	s_waitcnt vmcnt(1)
	v_mfma_f32_16x16x32_bf16 v[8:11], v[4:7], v[188:191], v[8:11]
	s_waitcnt vmcnt(0)
	s_nop 6
	v_add_f32_e32 v8, v228, v8
	v_mul_f32_e32 v8, 0xbfb8aa3b, v8
	v_exp_f32_e32 v8, v8
	s_nop 0
	v_add_f32_e32 v8, 1.0, v8
	v_div_scale_f32 v89, s[74:75], v8, v8, 1.0
	v_rcp_f32_e32 v141, v89
	s_nop 0
	v_fma_f32 v142, -v89, v141, 1.0
	v_fmac_f32_e32 v141, v142, v141
	v_div_scale_f32 v142, vcc, 1.0, v8, 1.0
	v_mul_f32_e32 v143, v142, v141
	v_fma_f32 v144, -v89, v143, v142
	v_fmac_f32_e32 v143, v144, v141
	v_fma_f32 v89, -v89, v143, v142
	v_div_fmas_f32 v89, v89, v141, v143
	v_div_fixup_f32 v8, v89, v8, 1.0
	v_mul_f32_e32 v89, 0x3f1b4598, v8
	v_cndmask_b32_e64 v8, v89, v8, s[50:51]
	v_cvt_f16_f32_e32 v8, v8
	ds_write_b16 v87, v8 offset:160
	v_add_f32_e32 v8, v228, v9
	v_mul_f32_e32 v8, 0xbfb8aa3b, v8
	v_exp_f32_e32 v8, v8
	s_nop 0
	v_add_f32_e32 v8, 1.0, v8
	v_div_scale_f32 v9, s[74:75], v8, v8, 1.0
	v_rcp_f32_e32 v89, v9
	s_nop 0
	v_fma_f32 v141, -v9, v89, 1.0
	v_fmac_f32_e32 v89, v141, v89
	v_div_scale_f32 v141, vcc, 1.0, v8, 1.0
	v_mul_f32_e32 v142, v141, v89
	v_fma_f32 v143, -v9, v142, v141
	v_fmac_f32_e32 v142, v143, v89
	v_fma_f32 v9, -v9, v142, v141
	v_div_fmas_f32 v9, v9, v89, v142
	v_div_fixup_f32 v8, v9, v8, 1.0
	v_mul_f32_e32 v9, 0x3f1b4598, v8
	v_cndmask_b32_e64 v8, v9, v8, s[50:51]
	v_cvt_f16_f32_e32 v8, v8
	ds_write_b16 v87, v8 offset:2208
	v_add_f32_e32 v8, v228, v10
	v_mul_f32_e32 v8, 0xbfb8aa3b, v8
	v_exp_f32_e32 v8, v8
	s_nop 0
	v_add_f32_e32 v8, 1.0, v8
	v_div_scale_f32 v9, s[74:75], v8, v8, 1.0
	v_rcp_f32_e32 v10, v9
	s_nop 0
	v_fma_f32 v89, -v9, v10, 1.0
	v_fmac_f32_e32 v10, v89, v10
	v_div_scale_f32 v89, vcc, 1.0, v8, 1.0
	v_mul_f32_e32 v141, v89, v10
	v_fma_f32 v142, -v9, v141, v89
	v_fmac_f32_e32 v141, v142, v10
	v_fma_f32 v9, -v9, v141, v89
	v_div_fmas_f32 v9, v9, v10, v141
	v_div_fixup_f32 v8, v9, v8, 1.0
	v_mul_f32_e32 v9, 0x3f1b4598, v8
	v_cndmask_b32_e64 v8, v9, v8, s[50:51]
	v_cvt_f16_f32_e32 v8, v8
	ds_write_b16 v87, v8 offset:4256
	v_add_f32_e32 v8, v228, v11
	v_mul_f32_e32 v8, 0xbfb8aa3b, v8
	v_exp_f32_e32 v8, v8
	s_nop 0
	v_add_f32_e32 v8, 1.0, v8
	v_div_scale_f32 v9, s[74:75], v8, v8, 1.0
	v_rcp_f32_e32 v10, v9
	s_nop 0
	v_fma_f32 v11, -v9, v10, 1.0
	v_fmac_f32_e32 v10, v11, v10
	v_div_scale_f32 v11, vcc, 1.0, v8, 1.0
	v_mul_f32_e32 v88, v11, v10
	v_fma_f32 v89, -v9, v88, v11
	v_fmac_f32_e32 v88, v89, v10
	v_fma_f32 v9, -v9, v88, v11
	v_div_fmas_f32 v9, v9, v10, v88
	v_div_fixup_f32 v8, v9, v8, 1.0
	v_mul_f32_e32 v9, 0x3f1b4598, v8
	v_cndmask_b32_e64 v8, v9, v8, s[50:51]
	v_cvt_f16_f32_e32 v8, v8
	ds_write_b16 v87, v8 offset:6304
	v_lshl_add_u64 v[8:9], v[70:71], 0, s[36:37]
	v_add_co_u32_e32 v88, vcc, s70, v8
	s_nop 1
	v_addc_co_u32_e32 v89, vcc, 0, v9, vcc
	s_waitcnt vmcnt(1)
	v_mfma_f32_16x16x32_bf16 v[8:11], v[0:3], v[192:195], 0
	s_waitcnt vmcnt(1)
	v_mfma_f32_16x16x32_bf16 v[8:11], v[4:7], v[216:219], v[8:11]
	s_waitcnt vmcnt(0)
; DEVI float sigm(float x) { return 1.f / (1.f + __expf(-x)); }
; DEVI void rwkv_pre_tile(int TID_, int BID_, PREF p, int g, int tile, char* shm) {
;     ...
; #pragma unroll
;       for (int nt = 0; nt < 8; ++nt) {
;         int col = w * 128 + 16 * nt + fr;
;         const u16* wp = lw + (size_t)lo * 65536 + (size_t)col * 64 + fq * 8;
;         bf16x8 b0 = *(const bf16x8*)wp, b1 = *(const bf16x8*)(wp + 32);
;         f32x4 acc = (f32x4){0.f, 0.f, 0.f, 0.f};
;         acc = __builtin_amdgcn_mfma_f32_16x16x32_bf16(a0, b0, acc, 0, 0, 0);
;         acc = __builtin_amdgcn_mfma_f32_16x16x32_bf16(a1, b1, acc, 0, 0, 0);
;         float bv = bias[col];
; #pragma unroll
;         for (int r = 0; r < 4; ++r) {
;           float sg = sigm(bv + acc[r]);
;           if (lo < 2) sg *= 0.60653066f;
;           resL[(size_t)(lo * 16 + fq * 4 + r) * 1024 + col] = f2h(sg);
;         }
;       }
	s_nop 6
	v_add_f32_e32 v8, v229, v8
	v_mul_f32_e32 v8, 0xbfb8aa3b, v8
	v_exp_f32_e32 v8, v8
	s_nop 0
	v_add_f32_e32 v8, 1.0, v8
	v_div_scale_f32 v89, s[74:75], v8, v8, 1.0
	v_rcp_f32_e32 v141, v89
	s_nop 0
	v_fma_f32 v142, -v89, v141, 1.0
	v_fmac_f32_e32 v141, v142, v141
	v_div_scale_f32 v142, vcc, 1.0, v8, 1.0
	v_mul_f32_e32 v143, v142, v141
	v_fma_f32 v144, -v89, v143, v142
	v_fmac_f32_e32 v143, v144, v141
	v_fma_f32 v89, -v89, v143, v142
	v_div_fmas_f32 v89, v89, v141, v143
	v_div_fixup_f32 v8, v89, v8, 1.0
	v_mul_f32_e32 v89, 0x3f1b4598, v8
	v_cndmask_b32_e64 v8, v89, v8, s[50:51]
	v_cvt_f16_f32_e32 v8, v8
	ds_write_b16 v87, v8 offset:192
	v_add_f32_e32 v8, v229, v9
	v_mul_f32_e32 v8, 0xbfb8aa3b, v8
	v_exp_f32_e32 v8, v8
	s_nop 0
	v_add_f32_e32 v8, 1.0, v8
	v_div_scale_f32 v9, s[74:75], v8, v8, 1.0
	v_rcp_f32_e32 v89, v9
	s_nop 0
	v_fma_f32 v141, -v9, v89, 1.0
	v_fmac_f32_e32 v89, v141, v89
	v_div_scale_f32 v141, vcc, 1.0, v8, 1.0
	v_mul_f32_e32 v142, v141, v89
	v_fma_f32 v143, -v9, v142, v141
	v_fmac_f32_e32 v142, v143, v89
	v_fma_f32 v9, -v9, v142, v141
	v_div_fmas_f32 v9, v9, v89, v142
	v_div_fixup_f32 v8, v9, v8, 1.0
	v_mul_f32_e32 v9, 0x3f1b4598, v8
	v_cndmask_b32_e64 v8, v9, v8, s[50:51]
	v_cvt_f16_f32_e32 v8, v8
	ds_write_b16 v87, v8 offset:2240
	v_add_f32_e32 v8, v229, v10
	v_mul_f32_e32 v8, 0xbfb8aa3b, v8
	v_exp_f32_e32 v8, v8
	s_nop 0
	v_add_f32_e32 v8, 1.0, v8
	v_div_scale_f32 v9, s[74:75], v8, v8, 1.0
	v_rcp_f32_e32 v10, v9
	s_nop 0
	v_fma_f32 v89, -v9, v10, 1.0
	v_fmac_f32_e32 v10, v89, v10
	v_div_scale_f32 v89, vcc, 1.0, v8, 1.0
	v_mul_f32_e32 v141, v89, v10
	v_fma_f32 v142, -v9, v141, v89
	v_fmac_f32_e32 v141, v142, v10
	v_fma_f32 v9, -v9, v141, v89
	v_div_fmas_f32 v9, v9, v10, v141
	v_div_fixup_f32 v8, v9, v8, 1.0
	v_mul_f32_e32 v9, 0x3f1b4598, v8
	v_cndmask_b32_e64 v8, v9, v8, s[50:51]
	v_cvt_f16_f32_e32 v8, v8
	ds_write_b16 v87, v8 offset:4288
	v_add_f32_e32 v8, v229, v11
	v_mul_f32_e32 v8, 0xbfb8aa3b, v8
	v_exp_f32_e32 v8, v8
	s_nop 0
	v_add_f32_e32 v8, 1.0, v8
	v_div_scale_f32 v9, s[74:75], v8, v8, 1.0
	v_rcp_f32_e32 v10, v9
	s_nop 0
	v_fma_f32 v11, -v9, v10, 1.0
	v_fmac_f32_e32 v10, v11, v10
	v_div_scale_f32 v11, vcc, 1.0, v8, 1.0
	v_mul_f32_e32 v88, v11, v10
	v_fma_f32 v89, -v9, v88, v11
	v_fmac_f32_e32 v88, v89, v10
	v_fma_f32 v9, -v9, v88, v11
	v_div_fmas_f32 v9, v9, v10, v88
	v_div_fixup_f32 v8, v9, v8, 1.0
	v_mul_f32_e32 v9, 0x3f1b4598, v8
	v_cndmask_b32_e64 v8, v9, v8, s[50:51]
	v_cvt_f16_f32_e32 v8, v8
	ds_write_b16 v87, v8 offset:6336
	v_lshl_add_u64 v[8:9], v[68:69], 0, s[36:37]
	v_add_co_u32_e32 v88, vcc, s70, v8
	s_add_u32 s36, s36, 0x20000
	s_nop 0
	v_addc_co_u32_e32 v89, vcc, 0, v9, vcc
	s_waitcnt vmcnt(1)
	v_mfma_f32_16x16x32_bf16 v[0:3], v[0:3], v[220:223], 0
	s_addc_u32 s37, s37, 0
	s_cmp_eq_u32 s36, 0x60000
	s_waitcnt vmcnt(0)
	v_mfma_f32_16x16x32_bf16 v[0:3], v[4:7], v[224:227], v[0:3]
	s_waitcnt vmcnt(0)
	s_nop 5
	v_add_f32_e32 v0, v230, v0
	v_mul_f32_e32 v0, 0xbfb8aa3b, v0
	v_exp_f32_e32 v0, v0
	s_nop 0
	v_add_f32_e32 v0, 1.0, v0
	v_div_scale_f32 v5, s[74:75], v0, v0, 1.0
	v_rcp_f32_e32 v6, v5
	s_nop 0
	v_fma_f32 v7, -v5, v6, 1.0
	v_fmac_f32_e32 v6, v7, v6
	v_div_scale_f32 v7, vcc, 1.0, v0, 1.0
	v_mul_f32_e32 v8, v7, v6
	v_fma_f32 v9, -v5, v8, v7
	v_fmac_f32_e32 v8, v9, v6
	v_fma_f32 v5, -v5, v8, v7
	v_div_fmas_f32 v5, v5, v6, v8
	v_div_fixup_f32 v0, v5, v0, 1.0
	v_mul_f32_e32 v5, 0x3f1b4598, v0
	v_cndmask_b32_e64 v0, v5, v0, s[50:51]
	v_cvt_f16_f32_e32 v0, v0
	ds_write_b16 v87, v0 offset:224
	v_add_f32_e32 v0, v230, v1
	v_mul_f32_e32 v0, 0xbfb8aa3b, v0
	v_exp_f32_e32 v0, v0
	s_nop 0
	v_add_f32_e32 v0, 1.0, v0
	v_div_scale_f32 v1, s[74:75], v0, v0, 1.0
	v_rcp_f32_e32 v5, v1
	s_nop 0
	v_fma_f32 v6, -v1, v5, 1.0
	v_fmac_f32_e32 v5, v6, v5
	v_div_scale_f32 v6, vcc, 1.0, v0, 1.0
	v_mul_f32_e32 v7, v6, v5
	v_fma_f32 v8, -v1, v7, v6
	v_fmac_f32_e32 v7, v8, v5
	v_fma_f32 v1, -v1, v7, v6
	v_div_fmas_f32 v1, v1, v5, v7
	v_div_fixup_f32 v0, v1, v0, 1.0
	v_mul_f32_e32 v1, 0x3f1b4598, v0
	v_cndmask_b32_e64 v0, v1, v0, s[50:51]
	v_cvt_f16_f32_e32 v0, v0
	ds_write_b16 v87, v0 offset:2272
	v_add_f32_e32 v0, v230, v2
	v_mul_f32_e32 v0, 0xbfb8aa3b, v0
	v_exp_f32_e32 v0, v0
	s_nop 0
	v_add_f32_e32 v0, 1.0, v0
	v_div_scale_f32 v1, s[74:75], v0, v0, 1.0
	v_rcp_f32_e32 v2, v1
	s_nop 0
	v_fma_f32 v5, -v1, v2, 1.0
	v_fmac_f32_e32 v2, v5, v2
	v_div_scale_f32 v5, vcc, 1.0, v0, 1.0
	v_mul_f32_e32 v6, v5, v2
	v_fma_f32 v7, -v1, v6, v5
	v_fmac_f32_e32 v6, v7, v2
	v_fma_f32 v1, -v1, v6, v5
	v_div_fmas_f32 v1, v1, v2, v6
	v_div_fixup_f32 v0, v1, v0, 1.0
	v_mul_f32_e32 v1, 0x3f1b4598, v0
	v_cndmask_b32_e64 v0, v1, v0, s[50:51]
	v_cvt_f16_f32_e32 v0, v0
	ds_write_b16 v87, v0 offset:4320
	v_add_f32_e32 v0, v230, v3
	v_mul_f32_e32 v0, 0xbfb8aa3b, v0
	v_exp_f32_e32 v0, v0
	s_nop 0
	v_add_f32_e32 v0, 1.0, v0
	v_div_scale_f32 v1, s[74:75], v0, v0, 1.0
	v_rcp_f32_e32 v2, v1
	s_nop 0
	v_fma_f32 v3, -v1, v2, 1.0
	v_fmac_f32_e32 v2, v3, v2
	v_div_scale_f32 v3, vcc, 1.0, v0, 1.0
	v_mul_f32_e32 v4, v3, v2
	v_fma_f32 v5, -v1, v4, v3
	v_fmac_f32_e32 v4, v5, v2
	v_fma_f32 v1, -v1, v4, v3
	v_div_fmas_f32 v1, v1, v2, v4
	v_div_fixup_f32 v0, v1, v0, 1.0
	v_mul_f32_e32 v1, 0x3f1b4598, v0
	v_cndmask_b32_e64 v0, v1, v0, s[50:51]
	v_cvt_f16_f32_e32 v0, v0
	ds_write_b16 v87, v0 offset:6368
	v_add_u32_e32 v87, 0x8000, v87
	s_cbranch_scc1 .LBB0_603

; DEVI void gemm_phase(int TID_, int BID_, const u16* __restrict__ A, const u16* __restrict__ Bt, int K, int nN, int epi, u16* Cb, int ldc,
;                      float* Cf, const float* resid, char* shm) {
;     ...
;   const int tid = TID_, wid = tid >> 6, lane = tid & 63, wr = wid >> 2, wc = wid & 3, fr = lane & 15, fq = lane >> 4;
;   const int ntiles = 64 * nN;
;   const int q = (ntiles + 7) >> 3;
;   const int xcd = BID_ & 7, slot = BID_ >> 3, nslot = gridDim.x >> 3;
;   int sR[4], sC[4];
; #pragma unroll
;   for (int i = 0; i < 4; ++i) stage_rc2(wid * 1024 + i * 8192 + lane * 16, sR[i], sC[i]);
;   const int nkt = K / 64;
;   const int swz_l = lds_byte2(fr, fq * 8);
;   const int a_lds = wr * 8 * 2048 + swz_l, b_lds = TILE_B + wc * 4 * 2048 + swz_l;
;   unsigned goff[4];
; #pragma unroll
;   for (int i = 0; i < 4; ++i) goff[i] = (unsigned)(sR[i] * K + sC[i]) * 2u;
;     ...
;   int brow, bcol, ok;
;   TILE_COORDS(slot, brow, bcol, ok);
;   const u16* Ab = A + (size_t)brow * K;
;   const u16* Bb = Bt + (size_t)bcol * K;
;   __syncthreads();
;   if (ok) { GLDS_STAGE(0, 0); GLDS_STAGE(1, 1); }
.LBB0_651:
	s_and_b32 s16, s90, 7
	s_lshl_b32 s28, s24, 3
	s_ashr_i32 s29, s90, 3
	s_mul_i32 s30, s28, s16
	s_lshl_b32 s27, s24, 6
	s_add_i32 s18, s30, s29
	s_cmp_lt_i32 s29, s28
	s_cselect_b64 s[16:17], -1, 0
	s_cmp_lt_i32 s18, s27
	s_cselect_b64 s[22:23], -1, 0
	s_and_b64 s[16:17], s[16:17], s[22:23]
	s_andn2_b64 vcc, exec, s[16:17]
	s_barrier
	s_cbranch_vccnz .LBB0_665
	s_cmp_ge_u32 s48, 4
	s_cbranch_scc0 .Lgemm_noprio
	s_setprio 1
.Lgemm_noprio:
	s_waitcnt vmcnt(8)
	v_ashrrev_i32_e32 v2, 6, v198
	v_lshlrev_b32_e32 v0, 4, v198
	v_and_b32_e32 v1, 32, v198
	v_lshlrev_b32_e32 v199, 10, v2
	v_bfe_u32 v3, v198, 2, 4
	v_bitop3_b32 v0, v0, v1, 48 bitop3:0x6c
	v_lshlrev_b32_e32 v1, 3, v2
	s_mov_b32 s19, 0x7ffffff0
	s_waitcnt vmcnt(7)
	v_lshlrev_b32_e32 v4, 5, v2
	v_lshrrev_b32_e32 v0, 1, v0
	v_and_or_b32 v1, v1, s19, v3
	v_add_u32_e32 v213, 0x2000, v199
	v_and_or_b32 v0, v4, 32, v0
	v_ashrrev_i32_e32 v4, 7, v213
	v_mul_lo_u32 v1, s26, v1
	v_and_or_b32 v4, v4, s19, v3
	v_add_u32_e32 v214, 0x4000, v199
	v_or_b32_e32 v1, v1, v0
	v_ashrrev_i32_e32 v5, 7, v214
	v_lshlrev_b32_e32 v216, 1, v1
	v_mul_lo_u32 v1, s26, v4
	v_cvt_f32_u32_e32 v4, s28
	v_and_or_b32 v5, v5, s19, v3
	v_add_u32_e32 v215, 0x6000, v199
	v_or_b32_e32 v1, v1, v0
	s_waitcnt vmcnt(6)
	v_ashrrev_i32_e32 v6, 7, v215
	v_lshlrev_b32_e32 v217, 1, v1
	v_mul_lo_u32 v1, s26, v5
	v_and_or_b32 v3, v6, s19, v3
	v_or_b32_e32 v1, v1, v0
	v_lshlrev_b32_e32 v218, 1, v1
	v_mul_lo_u32 v1, s26, v3
	v_rcp_iflag_f32_e32 v3, v4
	v_or_b32_e32 v0, v1, v0
	v_lshlrev_b32_e32 v219, 1, v0
	v_readfirstlane_b32 s44, v2
	s_nop 3
	s_lshr_b32 s45, s44, 1
	s_sub_u32 s45, s44, s45
	s_lshl_b32 s45, s45, 5
	s_mul_i32 s45, s45, s26
	s_and_b32 s44, s44, 1
	s_lshl_b32 s44, s44, 6
	s_sub_u32 s45, s45, s44
	v_add_u32_e32 v237, s45, v216
	s_lshl_b32 s44, s26, 8
	v_add_u32_e32 v238, s44, v237
	s_xor_b64 s[16:17], s[20:21], -1
	v_mul_f32_e32 v0, 0x4f7ffffe, v3
	v_cvt_u32_f32_e32 v0, v0
	s_sub_i32 s21, 0, s28
	s_abs_i32 s20, s18
	s_lshr_b32 s31, s26, 6
	v_readfirstlane_b32 s22, v0
	s_mul_i32 s21, s21, s22
	s_mul_hi_u32 s21, s22, s21
	s_add_i32 s34, s22, s21
	s_mul_hi_u32 s21, s20, s34
	s_mul_i32 s22, s21, s28
	s_sub_i32 s20, s20, s22
	s_ashr_i32 s19, s18, 31
	s_add_i32 s22, s21, 1
	s_sub_i32 s23, s20, s28
	s_cmp_ge_u32 s20, s28
	s_cselect_b32 s21, s22, s21
	s_cselect_b32 s20, s23, s20
	s_add_i32 s22, s21, 1
	s_cmp_ge_u32 s20, s28
	s_cselect_b32 s20, s22, s21
	s_xor_b32 s20, s20, s19
	s_sub_i32 s20, s20, s19
	s_mul_i32 s19, s20, s28
	s_sub_i32 s21, s18, s19
	s_lshl_b32 s18, s21, 5
	s_lshl_b32 s21, s21, 8
	s_and_b32 s42, s18, 0xffffff00
	s_ashr_i32 s18, s18, 31
	s_and_b32 s21, s21, 0x700
	s_lshl_b32 s20, s20, 11
	s_mul_i32 s18, s18, s26
	s_mul_hi_u32 s19, s42, s26
	s_or_b32 s43, s21, s20
	s_ashr_i32 s20, s20, 31
	s_add_i32 s19, s19, s18
	s_mul_i32 s18, s42, s26
	s_mul_i32 s20, s20, s26
	s_mul_hi_u32 s21, s43, s26
	s_add_i32 s21, s21, s20
	s_lshl_b64 s[22:23], s[18:19], 1
	s_mul_i32 s20, s43, s26
	s_add_u32 s22, s6, s22
	s_addc_u32 s23, s7, s23
	s_lshl_b64 s[24:25], s[20:21], 1
	s_add_u32 s24, s4, s24
	v_add_u32_e32 v220, 0x8000, v199
	v_readfirstlane_b32 s35, v199
	s_addc_u32 s25, s5, s25
	v_mov_b32_e32 v0, v216
	s_mov_b32 m0, s35
	v_readfirstlane_b32 s35, v220
	v_add_u32_e32 v221, 0xa000, v199
	global_load_lds_dwordx4 v0, s[24:25]
	s_mov_b32 m0, s35
	v_readfirstlane_b32 s35, v213
	global_load_lds_dwordx4 v0, s[22:23]
	v_mov_b32_e32 v0, v217
	s_mov_b32 m0, s35
	v_readfirstlane_b32 s35, v221
	v_add_u32_e32 v222, 0xc000, v199
	global_load_lds_dwordx4 v0, s[24:25]
	s_mov_b32 m0, s35
	v_readfirstlane_b32 s35, v214
	global_load_lds_dwordx4 v0, s[22:23]
	v_mov_b32_e32 v0, v218
	s_mov_b32 m0, s35
	v_readfirstlane_b32 s35, v222
	v_add_u32_e32 v223, 0xe000, v199
	global_load_lds_dwordx4 v0, s[24:25]
	s_mov_b32 m0, s35
	v_readfirstlane_b32 s35, v215
	global_load_lds_dwordx4 v0, s[22:23]
	v_mov_b32_e32 v0, v219
	s_mov_b32 m0, s35
	v_readfirstlane_b32 s35, v223
	v_add_u32_e32 v224, 0x10000, v199
	global_load_lds_dwordx4 v0, s[24:25]
	s_mov_b32 m0, s35
	v_mov_b32_e32 v196, v216
	s_mov_b64 s[74:75], s[36:37]
	global_load_lds_dwordx4 v0, s[22:23]
	s_mov_b64 s[36:37], 0x80
	v_lshl_add_u64 v[0:1], s[24:25], 0, v[196:197]
	v_readfirstlane_b32 s35, v224
	v_add_u32_e32 v225, 0x18000, v199
	v_lshl_add_u64 v[0:1], v[0:1], 0, s[36:37]
	s_mov_b32 m0, s35
	v_readfirstlane_b32 s35, v225
	global_load_lds_dwordx4 v[0:1], off
	v_lshl_add_u64 v[0:1], s[22:23], 0, v[196:197]
	v_lshl_add_u64 v[0:1], v[0:1], 0, s[36:37]
	s_mov_b32 m0, s35
	v_mov_b32_e32 v196, v217
	v_add_u32_e32 v226, 0x12000, v199
	global_load_lds_dwordx4 v[0:1], off
	v_readfirstlane_b32 s35, v226
	v_lshl_add_u64 v[0:1], s[24:25], 0, v[196:197]
	v_lshl_add_u64 v[0:1], v[0:1], 0, s[36:37]
	s_mov_b32 m0, s35
	v_add_u32_e32 v227, 0x1a000, v199
	global_load_lds_dwordx4 v[0:1], off
	v_lshl_add_u64 v[0:1], s[22:23], 0, v[196:197]
	v_readfirstlane_b32 s35, v227
	v_lshl_add_u64 v[0:1], v[0:1], 0, s[36:37]
	s_mov_b32 m0, s35
	v_mov_b32_e32 v196, v218
	v_add_u32_e32 v228, 0x14000, v199
	global_load_lds_dwordx4 v[0:1], off
	v_readfirstlane_b32 s35, v228
	v_lshl_add_u64 v[0:1], s[24:25], 0, v[196:197]
	v_lshl_add_u64 v[0:1], v[0:1], 0, s[36:37]
	s_mov_b32 m0, s35
	v_add_u32_e32 v229, 0x1c000, v199
	global_load_lds_dwordx4 v[0:1], off
	v_lshl_add_u64 v[0:1], s[22:23], 0, v[196:197]
	v_readfirstlane_b32 s35, v229
	v_lshl_add_u64 v[0:1], v[0:1], 0, s[36:37]
	s_mov_b32 m0, s35
	v_mov_b32_e32 v196, v219
	v_add_u32_e32 v230, 0x16000, v199
	global_load_lds_dwordx4 v[0:1], off
	v_add_u32_e32 v231, 0x1e000, v199
	v_lshl_add_u64 v[0:1], s[24:25], 0, v[196:197]
	v_readfirstlane_b32 s24, v230
	v_lshl_add_u64 v[0:1], v[0:1], 0, s[36:37]
	s_mov_b32 m0, s24
	s_lshl_b32 s35, s31, 16
	global_load_lds_dwordx4 v[0:1], off
	v_lshl_add_u64 v[0:1], s[22:23], 0, v[196:197]
	v_readfirstlane_b32 s22, v231
	v_lshl_add_u64 v[0:1], v[0:1], 0, s[36:37]
	s_mov_b32 m0, s22
	v_lshrrev_b32_e32 v3, 1, v198
	global_load_lds_dwordx4 v[0:1], off
	v_and_b32_e32 v0, 3, v2
	v_and_b32_e32 v2, 15, v198
	s_add_u32 s36, s4, 0x100
	v_ashrrev_i32_e32 v1, 8, v198
	v_and_b32_e32 v3, 24, v3
	v_lshlrev_b32_e32 v4, 6, v2
	v_lshlrev_b32_e32 v5, 2, v198
	s_addc_u32 s37, s5, 0
	s_mov_b64 s[88:89], s[38:39]
	v_lshl_or_b32 v4, v3, 1, v4
	v_and_b32_e32 v5, 32, v5
	v_lshlrev_b32_e32 v6, 14, v1
	v_lshlrev_b32_e32 v7, 13, v0
	s_add_u32 s38, s6, 0x100
	v_bitop3_b32 v232, v4, v7, v5 bitop3:0xde
	v_bitop3_b32 v233, v4, v6, v5 bitop3:0xde
	v_lshl_or_b32 v234, v1, 7, v2
	v_lshl_or_b32 v235, v0, 6, v3
	s_addc_u32 s39, s7, 0
	s_branch .LBB0_654

; #define WAIT_V0() asm volatile("s_waitcnt vmcnt(0)" ::: "memory")
; DEVI void gemm_phase(int TID_, int BID_, const u16* __restrict__ A, const u16* __restrict__ Bt, int K, int nN, int epi, u16* Cb, int ldc,
;                      float* Cf, const float* resid, char* shm) {
;     ...
;   WAIT_V0();
;   __syncthreads();
.LBB0_665:
	s_setprio 0
	s_waitcnt vmcnt(0)
	s_mov_b64 s[18:19], -1
	s_waitcnt vmcnt(0)
	s_barrier
